# all of: pipelined weight jobs, pool-fold batching, P1 rebuild, pool rewrite (gates waited lazily), scanner wait-fill, prep LoRA fragment hoist
# baseline (speedup 1.0000x reference)
.Lpool_sk14:
	v_add_u32_e32 v141, 0x3de00, v140
	global_load_dwordx4 v[60:63], v141, s[96:97]
	v_add_u32_e32 v141, 0x42000, v140
	global_load_dwordx4 v[64:67], v141, s[96:97]
	v_add_u32_e32 v141, 0x46200, v140
	global_load_dwordx4 v[68:71], v141, s[96:97]
	v_add_u32_e32 v141, 0x4a400, v140
	global_load_dwordx4 v[72:75], v141, s[96:97]
	v_add_u32_e32 v141, 0x4e600, v140
	global_load_dwordx4 v[76:79], v141, s[96:97]
	v_add_u32_e32 v141, 0x52800, v140
	global_load_dwordx4 v[80:83], v141, s[96:97]
	v_add_u32_e32 v141, 0x56a00, v140
	global_load_dwordx4 v[84:87], v141, s[96:97]
	v_add_u32_e32 v141, 0x5ac00, v140
	global_load_dwordx4 v[88:91], v141, s[96:97]
	v_add_u32_e32 v141, 0x3e200, v140
	global_load_dwordx4 v[92:95], v141, s[96:97]
	v_add_u32_e32 v141, 0x42400, v140
	global_load_dwordx4 v[96:99], v141, s[96:97]
	v_add_u32_e32 v141, 0x46600, v140
	global_load_dwordx4 v[100:103], v141, s[96:97]
	v_add_u32_e32 v141, 0x4a800, v140
	global_load_dwordx4 v[104:107], v141, s[96:97]
	v_add_u32_e32 v141, 0x4ea00, v140
	global_load_dwordx4 v[108:111], v141, s[96:97]
	v_add_u32_e32 v141, 0x52c00, v140
	global_load_dwordx4 v[112:115], v141, s[96:97]
	v_add_u32_e32 v141, 0x56e00, v140
	global_load_dwordx4 v[116:119], v141, s[96:97]
	v_add_u32_e32 v141, 0x5b000, v140
	global_load_dwordx4 v[120:123], v141, s[96:97]
	v_bfe_u32 v143, v226, 4, 2
	v_lshlrev_b32_e64 v142, v143, 2
	v_mov_b32_e32 v168, 0
	v_mov_b32_e32 v170, 0
	v_mov_b32_e32 v172, 0
	v_cmp_lt_u32_e32 vcc, 2, v142
	s_nop 1
	v_cndmask_b32_e32 v168, v168, v147, vcc
	v_cmp_lt_u32_e32 vcc, 4, v142
	s_nop 1
	v_cndmask_b32_e32 v170, v170, v147, vcc
	v_cmp_lt_u32_e32 vcc, 8, v142
	s_nop 1
	v_cndmask_b32_e32 v172, v172, v147, vcc
	s_add_i32 s0, s7, 1
	v_min_u32_e32 v132, s0, v142
	v_cvt_f32_u32_e32 v132, v132
	s_add_i32 s0, s7, 2
	v_min_u32_e32 v133, s0, v142
	v_cvt_f32_u32_e32 v133, v133
	v_div_scale_f32 v220, s[4:5], v132, v132, v147
	v_div_scale_f32 v225, s[4:5], v133, v133, v147
	v_rcp_f32_e32 v221, v220
	v_rcp_f32_e32 v144, v225
	s_nop 0
	v_fma_f32 v222, -v220, v221, 1.0
	v_fma_f32 v146, -v225, v144, 1.0
	v_fmac_f32_e32 v221, v222, v221
	v_fmac_f32_e32 v144, v146, v144
	v_div_scale_f32 v222, vcc, v147, v132, v147
	v_mul_f32_e32 v223, v222, v221
	v_fma_f32 v224, -v220, v223, v222
	v_fmac_f32_e32 v223, v224, v221
	v_fma_f32 v222, -v220, v223, v222
	s_nop 0
	v_div_fmas_f32 v222, v222, v221, v223
	v_div_scale_f32 v146, vcc, v147, v133, v147
	v_mul_f32_e32 v141, v146, v144
	v_fma_f32 v143, -v225, v141, v146
	v_fmac_f32_e32 v141, v143, v144
	v_fma_f32 v146, -v225, v141, v146
	v_div_fixup_f32 v152, v222, v132, v147
	v_div_fmas_f32 v146, v146, v144, v141
	s_nop 0
	v_div_fixup_f32 v154, v146, v133, v147
	s_add_i32 s0, s7, 3
	v_min_u32_e32 v132, s0, v142
	v_cvt_f32_u32_e32 v132, v132
	s_add_i32 s0, s7, 4
	v_min_u32_e32 v133, s0, v142
	v_cvt_f32_u32_e32 v133, v133
	v_div_scale_f32 v220, s[4:5], v132, v132, v147
	v_div_scale_f32 v225, s[4:5], v133, v133, v147
	v_rcp_f32_e32 v221, v220
	v_rcp_f32_e32 v144, v225
	s_nop 0
	v_fma_f32 v222, -v220, v221, 1.0
	v_fma_f32 v146, -v225, v144, 1.0
	v_fmac_f32_e32 v221, v222, v221
	v_fmac_f32_e32 v144, v146, v144
	v_div_scale_f32 v222, vcc, v147, v132, v147
	v_mul_f32_e32 v223, v222, v221
	v_fma_f32 v224, -v220, v223, v222
	v_fmac_f32_e32 v223, v224, v221
	v_fma_f32 v222, -v220, v223, v222
	s_nop 0
	v_div_fmas_f32 v222, v222, v221, v223
	v_div_scale_f32 v146, vcc, v147, v133, v147
	v_mul_f32_e32 v141, v146, v144
	v_fma_f32 v143, -v225, v141, v146
	v_fmac_f32_e32 v141, v143, v144
	v_fma_f32 v146, -v225, v141, v146
	v_div_fixup_f32 v156, v222, v132, v147
	v_div_fmas_f32 v146, v146, v144, v141
	s_nop 0
	v_div_fixup_f32 v158, v146, v133, v147
	s_add_i32 s0, s7, 5
	v_min_u32_e32 v132, s0, v142
	v_cvt_f32_u32_e32 v132, v132
	s_add_i32 s0, s7, 6
	v_min_u32_e32 v133, s0, v142
	v_cvt_f32_u32_e32 v133, v133
	v_div_scale_f32 v220, s[4:5], v132, v132, v147
	v_div_scale_f32 v225, s[4:5], v133, v133, v147
	v_rcp_f32_e32 v221, v220
	v_rcp_f32_e32 v144, v225
	s_nop 0
	v_fma_f32 v222, -v220, v221, 1.0
	v_fma_f32 v146, -v225, v144, 1.0
	v_fmac_f32_e32 v221, v222, v221
	v_fmac_f32_e32 v144, v146, v144
	v_div_scale_f32 v222, vcc, v147, v132, v147
	v_mul_f32_e32 v223, v222, v221
	v_fma_f32 v224, -v220, v223, v222
	v_fmac_f32_e32 v223, v224, v221
	v_fma_f32 v222, -v220, v223, v222
	s_nop 0
	v_div_fmas_f32 v222, v222, v221, v223
	v_div_scale_f32 v146, vcc, v147, v133, v147
	v_mul_f32_e32 v141, v146, v144
	v_fma_f32 v143, -v225, v141, v146
	v_fmac_f32_e32 v141, v143, v144
	v_fma_f32 v146, -v225, v141, v146
	v_div_fixup_f32 v160, v222, v132, v147
	v_div_fmas_f32 v146, v146, v144, v141
	s_nop 0
	v_div_fixup_f32 v162, v146, v133, v147
	s_add_i32 s0, s7, 7
	v_min_u32_e32 v132, s0, v142
	v_cvt_f32_u32_e32 v132, v132
	s_add_i32 s0, s7, 8
	v_min_u32_e32 v133, s0, v142
	v_cvt_f32_u32_e32 v133, v133
	v_div_scale_f32 v220, s[4:5], v132, v132, v147
	v_div_scale_f32 v225, s[4:5], v133, v133, v147
	v_rcp_f32_e32 v221, v220
	v_rcp_f32_e32 v144, v225
	s_nop 0
	v_fma_f32 v222, -v220, v221, 1.0
	v_fma_f32 v146, -v225, v144, 1.0
	v_fmac_f32_e32 v221, v222, v221
	v_fmac_f32_e32 v144, v146, v144
	v_div_scale_f32 v222, vcc, v147, v132, v147
	v_mul_f32_e32 v223, v222, v221
	v_fma_f32 v224, -v220, v223, v222
	v_fmac_f32_e32 v223, v224, v221
	v_fma_f32 v222, -v220, v223, v222
	s_nop 0
	v_div_fmas_f32 v222, v222, v221, v223
	v_div_scale_f32 v146, vcc, v147, v133, v147
	v_mul_f32_e32 v141, v146, v144
	v_fma_f32 v143, -v225, v141, v146
	v_fmac_f32_e32 v141, v143, v144
	v_fma_f32 v146, -v225, v141, v146
	v_div_fixup_f32 v164, v222, v132, v147
	v_div_fmas_f32 v146, v146, v144, v141
	s_nop 0
	v_div_fixup_f32 v166, v146, v133, v147
	s_waitcnt vmcnt(8)
	v_lshlrev_b32_e32 v174, 16, v0
	v_and_b32_e32 v175, 0xffff0000, v0
	v_lshlrev_b32_e32 v176, 16, v4
	v_and_b32_e32 v177, 0xffff0000, v4
	v_lshlrev_b32_e32 v178, 16, v8
	v_and_b32_e32 v179, 0xffff0000, v8
	v_lshlrev_b32_e32 v180, 16, v12
	v_and_b32_e32 v181, 0xffff0000, v12
	v_lshlrev_b32_e32 v182, 16, v16
	v_and_b32_e32 v183, 0xffff0000, v16
	v_lshlrev_b32_e32 v184, 16, v20
	v_and_b32_e32 v185, 0xffff0000, v20
	v_lshlrev_b32_e32 v186, 16, v24
	v_and_b32_e32 v187, 0xffff0000, v24
	v_lshlrev_b32_e32 v188, 16, v28
	v_and_b32_e32 v189, 0xffff0000, v28
	v_lshlrev_b32_e32 v190, 16, v32
	v_and_b32_e32 v191, 0xffff0000, v32
	v_lshlrev_b32_e32 v192, 16, v36
	v_and_b32_e32 v193, 0xffff0000, v36
	v_lshlrev_b32_e32 v194, 16, v40
	v_and_b32_e32 v195, 0xffff0000, v40
	v_lshlrev_b32_e32 v196, 16, v44
	v_and_b32_e32 v197, 0xffff0000, v44
	v_lshlrev_b32_e32 v198, 16, v48
	v_and_b32_e32 v199, 0xffff0000, v48
	v_lshlrev_b32_e32 v200, 16, v52
	v_and_b32_e32 v201, 0xffff0000, v52
	v_lshlrev_b32_e32 v202, 16, v56
	v_and_b32_e32 v203, 0xffff0000, v56
	v_lshlrev_b32_e32 v204, 16, v60
	v_and_b32_e32 v205, 0xffff0000, v60
	v_lshlrev_b32_e32 v206, 16, v64
	v_and_b32_e32 v207, 0xffff0000, v64
	v_lshlrev_b32_e32 v208, 16, v68
	v_and_b32_e32 v209, 0xffff0000, v68
	v_lshlrev_b32_e32 v210, 16, v72
	v_and_b32_e32 v211, 0xffff0000, v72
	v_lshlrev_b32_e32 v212, 16, v76
	v_and_b32_e32 v213, 0xffff0000, v76
	v_lshlrev_b32_e32 v214, 16, v80
	v_and_b32_e32 v215, 0xffff0000, v80
	v_lshlrev_b32_e32 v216, 16, v84
	v_and_b32_e32 v217, 0xffff0000, v84
	v_lshlrev_b32_e32 v218, 16, v88
	v_and_b32_e32 v219, 0xffff0000, v88
	v_pk_add_f32 v[218:219], v[218:219], v[216:217]
	v_pk_add_f32 v[216:217], v[216:217], v[214:215]
	v_pk_add_f32 v[214:215], v[214:215], v[212:213]
	v_pk_add_f32 v[212:213], v[212:213], v[210:211]
	v_pk_add_f32 v[210:211], v[210:211], v[208:209]
	v_pk_add_f32 v[208:209], v[208:209], v[206:207]
	v_pk_add_f32 v[206:207], v[206:207], v[204:205]
	v_pk_add_f32 v[204:205], v[204:205], v[202:203]
	v_pk_add_f32 v[202:203], v[202:203], v[200:201]
	v_pk_add_f32 v[200:201], v[200:201], v[198:199]
	v_pk_add_f32 v[198:199], v[198:199], v[196:197]
	v_pk_add_f32 v[196:197], v[196:197], v[194:195]
	v_pk_add_f32 v[194:195], v[194:195], v[192:193]
	v_pk_add_f32 v[192:193], v[192:193], v[190:191]
	v_pk_add_f32 v[190:191], v[190:191], v[188:189]
	v_pk_add_f32 v[188:189], v[188:189], v[186:187]
	v_pk_add_f32 v[186:187], v[186:187], v[184:185]
	v_pk_add_f32 v[184:185], v[184:185], v[182:183]
	v_pk_add_f32 v[182:183], v[182:183], v[180:181]
	v_pk_add_f32 v[180:181], v[180:181], v[178:179]
	v_pk_add_f32 v[178:179], v[178:179], v[176:177]
	v_pk_add_f32 v[176:177], v[176:177], v[174:175]
	v_pk_fma_f32 v[218:219], v[214:215], v[168:169], v[218:219] op_sel_hi:[1,0,1]
	v_pk_fma_f32 v[216:217], v[212:213], v[168:169], v[216:217] op_sel_hi:[1,0,1]
	v_pk_fma_f32 v[214:215], v[210:211], v[168:169], v[214:215] op_sel_hi:[1,0,1]
	v_pk_fma_f32 v[212:213], v[208:209], v[168:169], v[212:213] op_sel_hi:[1,0,1]
	v_pk_fma_f32 v[210:211], v[206:207], v[168:169], v[210:211] op_sel_hi:[1,0,1]
	v_pk_fma_f32 v[208:209], v[204:205], v[168:169], v[208:209] op_sel_hi:[1,0,1]
	v_pk_fma_f32 v[206:207], v[202:203], v[168:169], v[206:207] op_sel_hi:[1,0,1]
	v_pk_fma_f32 v[204:205], v[200:201], v[168:169], v[204:205] op_sel_hi:[1,0,1]
	v_pk_fma_f32 v[202:203], v[198:199], v[168:169], v[202:203] op_sel_hi:[1,0,1]
	v_pk_fma_f32 v[200:201], v[196:197], v[168:169], v[200:201] op_sel_hi:[1,0,1]
	v_pk_fma_f32 v[198:199], v[194:195], v[168:169], v[198:199] op_sel_hi:[1,0,1]
	v_pk_fma_f32 v[196:197], v[192:193], v[168:169], v[196:197] op_sel_hi:[1,0,1]
	v_pk_fma_f32 v[194:195], v[190:191], v[168:169], v[194:195] op_sel_hi:[1,0,1]
	v_pk_fma_f32 v[192:193], v[188:189], v[168:169], v[192:193] op_sel_hi:[1,0,1]
	v_pk_fma_f32 v[190:191], v[186:187], v[168:169], v[190:191] op_sel_hi:[1,0,1]
	v_pk_fma_f32 v[188:189], v[184:185], v[168:169], v[188:189] op_sel_hi:[1,0,1]
	v_pk_fma_f32 v[186:187], v[182:183], v[168:169], v[186:187] op_sel_hi:[1,0,1]
	v_pk_fma_f32 v[184:185], v[180:181], v[168:169], v[184:185] op_sel_hi:[1,0,1]
	v_pk_fma_f32 v[182:183], v[178:179], v[168:169], v[182:183] op_sel_hi:[1,0,1]
	v_pk_fma_f32 v[180:181], v[176:177], v[168:169], v[180:181] op_sel_hi:[1,0,1]
	v_pk_fma_f32 v[218:219], v[210:211], v[170:171], v[218:219] op_sel_hi:[1,0,1]
	v_pk_fma_f32 v[216:217], v[208:209], v[170:171], v[216:217] op_sel_hi:[1,0,1]
	v_pk_fma_f32 v[214:215], v[206:207], v[170:171], v[214:215] op_sel_hi:[1,0,1]
	v_pk_fma_f32 v[212:213], v[204:205], v[170:171], v[212:213] op_sel_hi:[1,0,1]
	v_pk_fma_f32 v[210:211], v[202:203], v[170:171], v[210:211] op_sel_hi:[1,0,1]
	v_pk_fma_f32 v[208:209], v[200:201], v[170:171], v[208:209] op_sel_hi:[1,0,1]
	v_pk_fma_f32 v[206:207], v[198:199], v[170:171], v[206:207] op_sel_hi:[1,0,1]
	v_pk_fma_f32 v[204:205], v[196:197], v[170:171], v[204:205] op_sel_hi:[1,0,1]
	v_pk_fma_f32 v[202:203], v[194:195], v[170:171], v[202:203] op_sel_hi:[1,0,1]
	v_pk_fma_f32 v[200:201], v[192:193], v[170:171], v[200:201] op_sel_hi:[1,0,1]
	v_pk_fma_f32 v[198:199], v[190:191], v[170:171], v[198:199] op_sel_hi:[1,0,1]
	v_pk_fma_f32 v[196:197], v[188:189], v[170:171], v[196:197] op_sel_hi:[1,0,1]
	v_pk_fma_f32 v[194:195], v[186:187], v[170:171], v[194:195] op_sel_hi:[1,0,1]
	v_pk_fma_f32 v[192:193], v[184:185], v[170:171], v[192:193] op_sel_hi:[1,0,1]
	v_pk_fma_f32 v[190:191], v[182:183], v[170:171], v[190:191] op_sel_hi:[1,0,1]
	v_pk_fma_f32 v[188:189], v[180:181], v[170:171], v[188:189] op_sel_hi:[1,0,1]
	v_pk_fma_f32 v[218:219], v[202:203], v[172:173], v[218:219] op_sel_hi:[1,0,1]
	v_pk_fma_f32 v[216:217], v[200:201], v[172:173], v[216:217] op_sel_hi:[1,0,1]
	v_pk_fma_f32 v[214:215], v[198:199], v[172:173], v[214:215] op_sel_hi:[1,0,1]
	v_pk_fma_f32 v[212:213], v[196:197], v[172:173], v[212:213] op_sel_hi:[1,0,1]
	v_pk_fma_f32 v[210:211], v[194:195], v[172:173], v[210:211] op_sel_hi:[1,0,1]
	v_pk_fma_f32 v[208:209], v[192:193], v[172:173], v[208:209] op_sel_hi:[1,0,1]
	v_pk_fma_f32 v[206:207], v[190:191], v[172:173], v[206:207] op_sel_hi:[1,0,1]
	v_pk_fma_f32 v[204:205], v[188:189], v[172:173], v[204:205] op_sel_hi:[1,0,1]
	s_waitcnt vmcnt(7)
	v_lshlrev_b32_e32 v132, 16, v60
	v_and_b32_e32 v133, 0xffff0000, v60
	v_lshlrev_b32_e32 v134, 16, v92
	v_and_b32_e32 v135, 0xffff0000, v92
	v_mul_f32_e32 v138, 0xbfb8aa3b, v134
	v_mul_f32_e32 v139, 0xbfb8aa3b, v135
	v_exp_f32_e32 v138, v138
	v_exp_f32_e32 v139, v139
	v_pk_fma_f32 v[136:137], v[204:205], v[152:153], v[132:133] op_sel_hi:[1,0,1] neg_lo:[0,0,1] neg_hi:[0,0,1]
	v_add_f32_e32 v138, 1.0, v138
	v_add_f32_e32 v139, 1.0, v139
	v_pk_mul_f32 v[136:137], v[124:125], v[136:137]
	v_div_scale_f32 v220, s[4:5], v138, v138, v134
	v_div_scale_f32 v225, s[4:5], v139, v139, v135
	v_rcp_f32_e32 v221, v220
	v_rcp_f32_e32 v144, v225
	s_nop 0
	v_fma_f32 v222, -v220, v221, 1.0
	v_fma_f32 v146, -v225, v144, 1.0
	v_fmac_f32_e32 v221, v222, v221
	v_fmac_f32_e32 v144, v146, v144
	v_div_scale_f32 v222, vcc, v134, v138, v134
	v_mul_f32_e32 v223, v222, v221
	v_fma_f32 v224, -v220, v223, v222
	v_fmac_f32_e32 v223, v224, v221
	v_fma_f32 v222, -v220, v223, v222
	s_nop 0
	v_div_fmas_f32 v222, v222, v221, v223
	v_div_scale_f32 v146, vcc, v135, v139, v135
	v_mul_f32_e32 v141, v146, v144
	v_fma_f32 v143, -v225, v141, v146
	v_fmac_f32_e32 v141, v143, v144
	v_fma_f32 v146, -v225, v141, v146
	v_div_fixup_f32 v134, v222, v138, v134
	v_div_fmas_f32 v146, v146, v144, v141
	s_nop 0
	v_div_fixup_f32 v135, v146, v139, v135
	v_pk_mul_f32 v[136:137], v[134:135], v[136:137]
	s_nop 0
	v_cvt_pk_bf16_f32 v92, v136, v137
	s_waitcnt vmcnt(6)
	v_lshlrev_b32_e32 v132, 16, v64
	v_and_b32_e32 v133, 0xffff0000, v64
	v_lshlrev_b32_e32 v134, 16, v96
	v_and_b32_e32 v135, 0xffff0000, v96
	v_mul_f32_e32 v138, 0xbfb8aa3b, v134
	v_mul_f32_e32 v139, 0xbfb8aa3b, v135
	v_exp_f32_e32 v138, v138
	v_exp_f32_e32 v139, v139
	v_pk_fma_f32 v[136:137], v[206:207], v[154:155], v[132:133] op_sel_hi:[1,0,1] neg_lo:[0,0,1] neg_hi:[0,0,1]
	v_add_f32_e32 v138, 1.0, v138
	v_add_f32_e32 v139, 1.0, v139
	v_pk_mul_f32 v[136:137], v[124:125], v[136:137]
	v_div_scale_f32 v220, s[4:5], v138, v138, v134
	v_div_scale_f32 v225, s[4:5], v139, v139, v135
	v_rcp_f32_e32 v221, v220
	v_rcp_f32_e32 v144, v225
	s_nop 0
	v_fma_f32 v222, -v220, v221, 1.0
	v_fma_f32 v146, -v225, v144, 1.0
	v_fmac_f32_e32 v221, v222, v221
	v_fmac_f32_e32 v144, v146, v144
	v_div_scale_f32 v222, vcc, v134, v138, v134
	v_mul_f32_e32 v223, v222, v221
	v_fma_f32 v224, -v220, v223, v222
	v_fmac_f32_e32 v223, v224, v221
	v_fma_f32 v222, -v220, v223, v222
	s_nop 0
	v_div_fmas_f32 v222, v222, v221, v223
	v_div_scale_f32 v146, vcc, v135, v139, v135
	v_mul_f32_e32 v141, v146, v144
	v_fma_f32 v143, -v225, v141, v146
	v_fmac_f32_e32 v141, v143, v144
	v_fma_f32 v146, -v225, v141, v146
	v_div_fixup_f32 v134, v222, v138, v134
	v_div_fmas_f32 v146, v146, v144, v141
	s_nop 0
	v_div_fixup_f32 v135, v146, v139, v135
	v_pk_mul_f32 v[136:137], v[134:135], v[136:137]
	s_nop 0
	v_cvt_pk_bf16_f32 v96, v136, v137
	s_waitcnt vmcnt(5)
	v_lshlrev_b32_e32 v132, 16, v68
	v_and_b32_e32 v133, 0xffff0000, v68
	v_lshlrev_b32_e32 v134, 16, v100
	v_and_b32_e32 v135, 0xffff0000, v100
	v_mul_f32_e32 v138, 0xbfb8aa3b, v134
	v_mul_f32_e32 v139, 0xbfb8aa3b, v135
	v_exp_f32_e32 v138, v138
	v_exp_f32_e32 v139, v139
	v_pk_fma_f32 v[136:137], v[208:209], v[156:157], v[132:133] op_sel_hi:[1,0,1] neg_lo:[0,0,1] neg_hi:[0,0,1]
	v_add_f32_e32 v138, 1.0, v138
	v_add_f32_e32 v139, 1.0, v139
	v_pk_mul_f32 v[136:137], v[124:125], v[136:137]
	v_div_scale_f32 v220, s[4:5], v138, v138, v134
	v_div_scale_f32 v225, s[4:5], v139, v139, v135
	v_rcp_f32_e32 v221, v220
	v_rcp_f32_e32 v144, v225
	s_nop 0
	v_fma_f32 v222, -v220, v221, 1.0
	v_fma_f32 v146, -v225, v144, 1.0
	v_fmac_f32_e32 v221, v222, v221
	v_fmac_f32_e32 v144, v146, v144
	v_div_scale_f32 v222, vcc, v134, v138, v134
	v_mul_f32_e32 v223, v222, v221
	v_fma_f32 v224, -v220, v223, v222
	v_fmac_f32_e32 v223, v224, v221
	v_fma_f32 v222, -v220, v223, v222
	s_nop 0
	v_div_fmas_f32 v222, v222, v221, v223
	v_div_scale_f32 v146, vcc, v135, v139, v135
	v_mul_f32_e32 v141, v146, v144
	v_fma_f32 v143, -v225, v141, v146
	v_fmac_f32_e32 v141, v143, v144
	v_fma_f32 v146, -v225, v141, v146
	v_div_fixup_f32 v134, v222, v138, v134
	v_div_fmas_f32 v146, v146, v144, v141
	s_nop 0
	v_div_fixup_f32 v135, v146, v139, v135
	v_pk_mul_f32 v[136:137], v[134:135], v[136:137]
	s_nop 0
	v_cvt_pk_bf16_f32 v100, v136, v137
	s_waitcnt vmcnt(4)
	v_lshlrev_b32_e32 v132, 16, v72
	v_and_b32_e32 v133, 0xffff0000, v72
	v_lshlrev_b32_e32 v134, 16, v104
	v_and_b32_e32 v135, 0xffff0000, v104
	v_mul_f32_e32 v138, 0xbfb8aa3b, v134
	v_mul_f32_e32 v139, 0xbfb8aa3b, v135
	v_exp_f32_e32 v138, v138
	v_exp_f32_e32 v139, v139
	v_pk_fma_f32 v[136:137], v[210:211], v[158:159], v[132:133] op_sel_hi:[1,0,1] neg_lo:[0,0,1] neg_hi:[0,0,1]
	v_add_f32_e32 v138, 1.0, v138
	v_add_f32_e32 v139, 1.0, v139
	v_pk_mul_f32 v[136:137], v[124:125], v[136:137]
	v_div_scale_f32 v220, s[4:5], v138, v138, v134
	v_div_scale_f32 v225, s[4:5], v139, v139, v135
	v_rcp_f32_e32 v221, v220
	v_rcp_f32_e32 v144, v225
	s_nop 0
	v_fma_f32 v222, -v220, v221, 1.0
	v_fma_f32 v146, -v225, v144, 1.0
	v_fmac_f32_e32 v221, v222, v221
	v_fmac_f32_e32 v144, v146, v144
	v_div_scale_f32 v222, vcc, v134, v138, v134
	v_mul_f32_e32 v223, v222, v221
	v_fma_f32 v224, -v220, v223, v222
	v_fmac_f32_e32 v223, v224, v221
	v_fma_f32 v222, -v220, v223, v222
	s_nop 0
	v_div_fmas_f32 v222, v222, v221, v223
	v_div_scale_f32 v146, vcc, v135, v139, v135
	v_mul_f32_e32 v141, v146, v144
	v_fma_f32 v143, -v225, v141, v146
	v_fmac_f32_e32 v141, v143, v144
	v_fma_f32 v146, -v225, v141, v146
	v_div_fixup_f32 v134, v222, v138, v134
	v_div_fmas_f32 v146, v146, v144, v141
	s_nop 0
	v_div_fixup_f32 v135, v146, v139, v135
	v_pk_mul_f32 v[136:137], v[134:135], v[136:137]
	s_nop 0
	v_cvt_pk_bf16_f32 v104, v136, v137
	s_waitcnt vmcnt(3)
	v_lshlrev_b32_e32 v132, 16, v76
	v_and_b32_e32 v133, 0xffff0000, v76
	v_lshlrev_b32_e32 v134, 16, v108
	v_and_b32_e32 v135, 0xffff0000, v108
	v_mul_f32_e32 v138, 0xbfb8aa3b, v134
	v_mul_f32_e32 v139, 0xbfb8aa3b, v135
	v_exp_f32_e32 v138, v138
	v_exp_f32_e32 v139, v139
	v_pk_fma_f32 v[136:137], v[212:213], v[160:161], v[132:133] op_sel_hi:[1,0,1] neg_lo:[0,0,1] neg_hi:[0,0,1]
	v_add_f32_e32 v138, 1.0, v138
	v_add_f32_e32 v139, 1.0, v139
	v_pk_mul_f32 v[136:137], v[124:125], v[136:137]
	v_div_scale_f32 v220, s[4:5], v138, v138, v134
	v_div_scale_f32 v225, s[4:5], v139, v139, v135
	v_rcp_f32_e32 v221, v220
	v_rcp_f32_e32 v144, v225
	s_nop 0
	v_fma_f32 v222, -v220, v221, 1.0
	v_fma_f32 v146, -v225, v144, 1.0
	v_fmac_f32_e32 v221, v222, v221
	v_fmac_f32_e32 v144, v146, v144
	v_div_scale_f32 v222, vcc, v134, v138, v134
	v_mul_f32_e32 v223, v222, v221
	v_fma_f32 v224, -v220, v223, v222
	v_fmac_f32_e32 v223, v224, v221
	v_fma_f32 v222, -v220, v223, v222
	s_nop 0
	v_div_fmas_f32 v222, v222, v221, v223
	v_div_scale_f32 v146, vcc, v135, v139, v135
	v_mul_f32_e32 v141, v146, v144
	v_fma_f32 v143, -v225, v141, v146
	v_fmac_f32_e32 v141, v143, v144
	v_fma_f32 v146, -v225, v141, v146
	v_div_fixup_f32 v134, v222, v138, v134
	v_div_fmas_f32 v146, v146, v144, v141
	s_nop 0
	v_div_fixup_f32 v135, v146, v139, v135
	v_pk_mul_f32 v[136:137], v[134:135], v[136:137]
	s_nop 0
	v_cvt_pk_bf16_f32 v108, v136, v137
	s_waitcnt vmcnt(2)
	v_lshlrev_b32_e32 v132, 16, v80
	v_and_b32_e32 v133, 0xffff0000, v80
	v_lshlrev_b32_e32 v134, 16, v112
	v_and_b32_e32 v135, 0xffff0000, v112
	v_mul_f32_e32 v138, 0xbfb8aa3b, v134
	v_mul_f32_e32 v139, 0xbfb8aa3b, v135
	v_exp_f32_e32 v138, v138
	v_exp_f32_e32 v139, v139
	v_pk_fma_f32 v[136:137], v[214:215], v[162:163], v[132:133] op_sel_hi:[1,0,1] neg_lo:[0,0,1] neg_hi:[0,0,1]
	v_add_f32_e32 v138, 1.0, v138
	v_add_f32_e32 v139, 1.0, v139
	v_pk_mul_f32 v[136:137], v[124:125], v[136:137]
	v_div_scale_f32 v220, s[4:5], v138, v138, v134
	v_div_scale_f32 v225, s[4:5], v139, v139, v135
	v_rcp_f32_e32 v221, v220
	v_rcp_f32_e32 v144, v225
	s_nop 0
	v_fma_f32 v222, -v220, v221, 1.0
	v_fma_f32 v146, -v225, v144, 1.0
	v_fmac_f32_e32 v221, v222, v221
	v_fmac_f32_e32 v144, v146, v144
	v_div_scale_f32 v222, vcc, v134, v138, v134
	v_mul_f32_e32 v223, v222, v221
	v_fma_f32 v224, -v220, v223, v222
	v_fmac_f32_e32 v223, v224, v221
	v_fma_f32 v222, -v220, v223, v222
	s_nop 0
	v_div_fmas_f32 v222, v222, v221, v223
	v_div_scale_f32 v146, vcc, v135, v139, v135
	v_mul_f32_e32 v141, v146, v144
	v_fma_f32 v143, -v225, v141, v146
	v_fmac_f32_e32 v141, v143, v144
	v_fma_f32 v146, -v225, v141, v146
	v_div_fixup_f32 v134, v222, v138, v134
	v_div_fmas_f32 v146, v146, v144, v141
	s_nop 0
	v_div_fixup_f32 v135, v146, v139, v135
	v_pk_mul_f32 v[136:137], v[134:135], v[136:137]
	s_nop 0
	v_cvt_pk_bf16_f32 v112, v136, v137
	s_waitcnt vmcnt(1)
	v_lshlrev_b32_e32 v132, 16, v84
	v_and_b32_e32 v133, 0xffff0000, v84
	v_lshlrev_b32_e32 v134, 16, v116
	v_and_b32_e32 v135, 0xffff0000, v116
	v_mul_f32_e32 v138, 0xbfb8aa3b, v134
	v_mul_f32_e32 v139, 0xbfb8aa3b, v135
	v_exp_f32_e32 v138, v138
	v_exp_f32_e32 v139, v139
	v_pk_fma_f32 v[136:137], v[216:217], v[164:165], v[132:133] op_sel_hi:[1,0,1] neg_lo:[0,0,1] neg_hi:[0,0,1]
	v_add_f32_e32 v138, 1.0, v138
	v_add_f32_e32 v139, 1.0, v139
	v_pk_mul_f32 v[136:137], v[124:125], v[136:137]
	v_div_scale_f32 v220, s[4:5], v138, v138, v134
	v_div_scale_f32 v225, s[4:5], v139, v139, v135
	v_rcp_f32_e32 v221, v220
	v_rcp_f32_e32 v144, v225
	s_nop 0
	v_fma_f32 v222, -v220, v221, 1.0
	v_fma_f32 v146, -v225, v144, 1.0
	v_fmac_f32_e32 v221, v222, v221
	v_fmac_f32_e32 v144, v146, v144
	v_div_scale_f32 v222, vcc, v134, v138, v134
	v_mul_f32_e32 v223, v222, v221
	v_fma_f32 v224, -v220, v223, v222
	v_fmac_f32_e32 v223, v224, v221
	v_fma_f32 v222, -v220, v223, v222
	s_nop 0
	v_div_fmas_f32 v222, v222, v221, v223
	v_div_scale_f32 v146, vcc, v135, v139, v135
	v_mul_f32_e32 v141, v146, v144
	v_fma_f32 v143, -v225, v141, v146
	v_fmac_f32_e32 v141, v143, v144
	v_fma_f32 v146, -v225, v141, v146
	v_div_fixup_f32 v134, v222, v138, v134
	v_div_fmas_f32 v146, v146, v144, v141
	s_nop 0
	v_div_fixup_f32 v135, v146, v139, v135
	v_pk_mul_f32 v[136:137], v[134:135], v[136:137]
	s_nop 0
	v_cvt_pk_bf16_f32 v116, v136, v137
	s_waitcnt vmcnt(0)
	v_lshlrev_b32_e32 v132, 16, v88
	v_and_b32_e32 v133, 0xffff0000, v88
	v_lshlrev_b32_e32 v134, 16, v120
	v_and_b32_e32 v135, 0xffff0000, v120
	v_mul_f32_e32 v138, 0xbfb8aa3b, v134
	v_mul_f32_e32 v139, 0xbfb8aa3b, v135
	v_exp_f32_e32 v138, v138
	v_exp_f32_e32 v139, v139
	v_pk_fma_f32 v[136:137], v[218:219], v[166:167], v[132:133] op_sel_hi:[1,0,1] neg_lo:[0,0,1] neg_hi:[0,0,1]
	v_add_f32_e32 v138, 1.0, v138
	v_add_f32_e32 v139, 1.0, v139
	v_pk_mul_f32 v[136:137], v[124:125], v[136:137]
	v_div_scale_f32 v220, s[4:5], v138, v138, v134
	v_div_scale_f32 v225, s[4:5], v139, v139, v135
	v_rcp_f32_e32 v221, v220
	v_rcp_f32_e32 v144, v225
	s_nop 0
	v_fma_f32 v222, -v220, v221, 1.0
	v_fma_f32 v146, -v225, v144, 1.0
	v_fmac_f32_e32 v221, v222, v221
	v_fmac_f32_e32 v144, v146, v144
	v_div_scale_f32 v222, vcc, v134, v138, v134
	v_mul_f32_e32 v223, v222, v221
	v_fma_f32 v224, -v220, v223, v222
	v_fmac_f32_e32 v223, v224, v221
	v_fma_f32 v222, -v220, v223, v222
	s_nop 0
	v_div_fmas_f32 v222, v222, v221, v223
	v_div_scale_f32 v146, vcc, v135, v139, v135
	v_mul_f32_e32 v141, v146, v144
	v_fma_f32 v143, -v225, v141, v146
	v_fmac_f32_e32 v141, v143, v144
	v_fma_f32 v146, -v225, v141, v146
	v_div_fixup_f32 v134, v222, v138, v134
	v_div_fmas_f32 v146, v146, v144, v141
	s_nop 0
	v_div_fixup_f32 v135, v146, v139, v135
	v_pk_mul_f32 v[136:137], v[134:135], v[136:137]
	s_nop 0
	v_cvt_pk_bf16_f32 v120, v136, v137
	v_lshlrev_b32_e32 v174, 16, v1
	v_and_b32_e32 v175, 0xffff0000, v1
	v_lshlrev_b32_e32 v176, 16, v5
	v_and_b32_e32 v177, 0xffff0000, v5
	v_lshlrev_b32_e32 v178, 16, v9
	v_and_b32_e32 v179, 0xffff0000, v9
	v_lshlrev_b32_e32 v180, 16, v13
	v_and_b32_e32 v181, 0xffff0000, v13
	v_lshlrev_b32_e32 v182, 16, v17
	v_and_b32_e32 v183, 0xffff0000, v17
	v_lshlrev_b32_e32 v184, 16, v21
	v_and_b32_e32 v185, 0xffff0000, v21
	v_lshlrev_b32_e32 v186, 16, v25
	v_and_b32_e32 v187, 0xffff0000, v25
	v_lshlrev_b32_e32 v188, 16, v29
	v_and_b32_e32 v189, 0xffff0000, v29
	v_lshlrev_b32_e32 v190, 16, v33
	v_and_b32_e32 v191, 0xffff0000, v33
	v_lshlrev_b32_e32 v192, 16, v37
	v_and_b32_e32 v193, 0xffff0000, v37
	v_lshlrev_b32_e32 v194, 16, v41
	v_and_b32_e32 v195, 0xffff0000, v41
	v_lshlrev_b32_e32 v196, 16, v45
	v_and_b32_e32 v197, 0xffff0000, v45
	v_lshlrev_b32_e32 v198, 16, v49
	v_and_b32_e32 v199, 0xffff0000, v49
	v_lshlrev_b32_e32 v200, 16, v53
	v_and_b32_e32 v201, 0xffff0000, v53
	v_lshlrev_b32_e32 v202, 16, v57
	v_and_b32_e32 v203, 0xffff0000, v57
	v_lshlrev_b32_e32 v204, 16, v61
	v_and_b32_e32 v205, 0xffff0000, v61
	v_lshlrev_b32_e32 v206, 16, v65
	v_and_b32_e32 v207, 0xffff0000, v65
	v_lshlrev_b32_e32 v208, 16, v69
	v_and_b32_e32 v209, 0xffff0000, v69
	v_lshlrev_b32_e32 v210, 16, v73
	v_and_b32_e32 v211, 0xffff0000, v73
	v_lshlrev_b32_e32 v212, 16, v77
	v_and_b32_e32 v213, 0xffff0000, v77
	v_lshlrev_b32_e32 v214, 16, v81
	v_and_b32_e32 v215, 0xffff0000, v81
	v_lshlrev_b32_e32 v216, 16, v85
	v_and_b32_e32 v217, 0xffff0000, v85
	v_lshlrev_b32_e32 v218, 16, v89
	v_and_b32_e32 v219, 0xffff0000, v89
	v_pk_add_f32 v[218:219], v[218:219], v[216:217]
	v_pk_add_f32 v[216:217], v[216:217], v[214:215]
	v_pk_add_f32 v[214:215], v[214:215], v[212:213]
	v_pk_add_f32 v[212:213], v[212:213], v[210:211]
	v_pk_add_f32 v[210:211], v[210:211], v[208:209]
	v_pk_add_f32 v[208:209], v[208:209], v[206:207]
	v_pk_add_f32 v[206:207], v[206:207], v[204:205]
	v_pk_add_f32 v[204:205], v[204:205], v[202:203]
	v_pk_add_f32 v[202:203], v[202:203], v[200:201]
	v_pk_add_f32 v[200:201], v[200:201], v[198:199]
	v_pk_add_f32 v[198:199], v[198:199], v[196:197]
	v_pk_add_f32 v[196:197], v[196:197], v[194:195]
	v_pk_add_f32 v[194:195], v[194:195], v[192:193]
	v_pk_add_f32 v[192:193], v[192:193], v[190:191]
	v_pk_add_f32 v[190:191], v[190:191], v[188:189]
	v_pk_add_f32 v[188:189], v[188:189], v[186:187]
	v_pk_add_f32 v[186:187], v[186:187], v[184:185]
	v_pk_add_f32 v[184:185], v[184:185], v[182:183]
	v_pk_add_f32 v[182:183], v[182:183], v[180:181]
	v_pk_add_f32 v[180:181], v[180:181], v[178:179]
	v_pk_add_f32 v[178:179], v[178:179], v[176:177]
	v_pk_add_f32 v[176:177], v[176:177], v[174:175]
	v_pk_fma_f32 v[218:219], v[214:215], v[168:169], v[218:219] op_sel_hi:[1,0,1]
	v_pk_fma_f32 v[216:217], v[212:213], v[168:169], v[216:217] op_sel_hi:[1,0,1]
	v_pk_fma_f32 v[214:215], v[210:211], v[168:169], v[214:215] op_sel_hi:[1,0,1]
	v_pk_fma_f32 v[212:213], v[208:209], v[168:169], v[212:213] op_sel_hi:[1,0,1]
	v_pk_fma_f32 v[210:211], v[206:207], v[168:169], v[210:211] op_sel_hi:[1,0,1]
	v_pk_fma_f32 v[208:209], v[204:205], v[168:169], v[208:209] op_sel_hi:[1,0,1]
	v_pk_fma_f32 v[206:207], v[202:203], v[168:169], v[206:207] op_sel_hi:[1,0,1]
	v_pk_fma_f32 v[204:205], v[200:201], v[168:169], v[204:205] op_sel_hi:[1,0,1]
	v_pk_fma_f32 v[202:203], v[198:199], v[168:169], v[202:203] op_sel_hi:[1,0,1]
	v_pk_fma_f32 v[200:201], v[196:197], v[168:169], v[200:201] op_sel_hi:[1,0,1]
	v_pk_fma_f32 v[198:199], v[194:195], v[168:169], v[198:199] op_sel_hi:[1,0,1]
	v_pk_fma_f32 v[196:197], v[192:193], v[168:169], v[196:197] op_sel_hi:[1,0,1]
	v_pk_fma_f32 v[194:195], v[190:191], v[168:169], v[194:195] op_sel_hi:[1,0,1]
	v_pk_fma_f32 v[192:193], v[188:189], v[168:169], v[192:193] op_sel_hi:[1,0,1]
	v_pk_fma_f32 v[190:191], v[186:187], v[168:169], v[190:191] op_sel_hi:[1,0,1]
	v_pk_fma_f32 v[188:189], v[184:185], v[168:169], v[188:189] op_sel_hi:[1,0,1]
	v_pk_fma_f32 v[186:187], v[182:183], v[168:169], v[186:187] op_sel_hi:[1,0,1]
	v_pk_fma_f32 v[184:185], v[180:181], v[168:169], v[184:185] op_sel_hi:[1,0,1]
	v_pk_fma_f32 v[182:183], v[178:179], v[168:169], v[182:183] op_sel_hi:[1,0,1]
	v_pk_fma_f32 v[180:181], v[176:177], v[168:169], v[180:181] op_sel_hi:[1,0,1]
	v_pk_fma_f32 v[218:219], v[210:211], v[170:171], v[218:219] op_sel_hi:[1,0,1]
	v_pk_fma_f32 v[216:217], v[208:209], v[170:171], v[216:217] op_sel_hi:[1,0,1]
	v_pk_fma_f32 v[214:215], v[206:207], v[170:171], v[214:215] op_sel_hi:[1,0,1]
	v_pk_fma_f32 v[212:213], v[204:205], v[170:171], v[212:213] op_sel_hi:[1,0,1]
	v_pk_fma_f32 v[210:211], v[202:203], v[170:171], v[210:211] op_sel_hi:[1,0,1]
	v_pk_fma_f32 v[208:209], v[200:201], v[170:171], v[208:209] op_sel_hi:[1,0,1]
	v_pk_fma_f32 v[206:207], v[198:199], v[170:171], v[206:207] op_sel_hi:[1,0,1]
	v_pk_fma_f32 v[204:205], v[196:197], v[170:171], v[204:205] op_sel_hi:[1,0,1]
	v_pk_fma_f32 v[202:203], v[194:195], v[170:171], v[202:203] op_sel_hi:[1,0,1]
	v_pk_fma_f32 v[200:201], v[192:193], v[170:171], v[200:201] op_sel_hi:[1,0,1]
	v_pk_fma_f32 v[198:199], v[190:191], v[170:171], v[198:199] op_sel_hi:[1,0,1]
	v_pk_fma_f32 v[196:197], v[188:189], v[170:171], v[196:197] op_sel_hi:[1,0,1]
	v_pk_fma_f32 v[194:195], v[186:187], v[170:171], v[194:195] op_sel_hi:[1,0,1]
	v_pk_fma_f32 v[192:193], v[184:185], v[170:171], v[192:193] op_sel_hi:[1,0,1]
	v_pk_fma_f32 v[190:191], v[182:183], v[170:171], v[190:191] op_sel_hi:[1,0,1]
	v_pk_fma_f32 v[188:189], v[180:181], v[170:171], v[188:189] op_sel_hi:[1,0,1]
	v_pk_fma_f32 v[218:219], v[202:203], v[172:173], v[218:219] op_sel_hi:[1,0,1]
	v_pk_fma_f32 v[216:217], v[200:201], v[172:173], v[216:217] op_sel_hi:[1,0,1]
	v_pk_fma_f32 v[214:215], v[198:199], v[172:173], v[214:215] op_sel_hi:[1,0,1]
	v_pk_fma_f32 v[212:213], v[196:197], v[172:173], v[212:213] op_sel_hi:[1,0,1]
	v_pk_fma_f32 v[210:211], v[194:195], v[172:173], v[210:211] op_sel_hi:[1,0,1]
	v_pk_fma_f32 v[208:209], v[192:193], v[172:173], v[208:209] op_sel_hi:[1,0,1]
	v_pk_fma_f32 v[206:207], v[190:191], v[172:173], v[206:207] op_sel_hi:[1,0,1]
	v_pk_fma_f32 v[204:205], v[188:189], v[172:173], v[204:205] op_sel_hi:[1,0,1]
	v_lshlrev_b32_e32 v132, 16, v61
	v_and_b32_e32 v133, 0xffff0000, v61
	v_lshlrev_b32_e32 v134, 16, v93
	v_and_b32_e32 v135, 0xffff0000, v93
	v_mul_f32_e32 v138, 0xbfb8aa3b, v134
	v_mul_f32_e32 v139, 0xbfb8aa3b, v135
	v_exp_f32_e32 v138, v138
	v_exp_f32_e32 v139, v139
	v_pk_fma_f32 v[136:137], v[204:205], v[152:153], v[132:133] op_sel_hi:[1,0,1] neg_lo:[0,0,1] neg_hi:[0,0,1]
	v_add_f32_e32 v138, 1.0, v138
	v_add_f32_e32 v139, 1.0, v139
	v_pk_mul_f32 v[136:137], v[126:127], v[136:137]
	v_div_scale_f32 v220, s[4:5], v138, v138, v134
	v_div_scale_f32 v225, s[4:5], v139, v139, v135
	v_rcp_f32_e32 v221, v220
	v_rcp_f32_e32 v144, v225
	s_nop 0
	v_fma_f32 v222, -v220, v221, 1.0
	v_fma_f32 v146, -v225, v144, 1.0
	v_fmac_f32_e32 v221, v222, v221
	v_fmac_f32_e32 v144, v146, v144
	v_div_scale_f32 v222, vcc, v134, v138, v134
	v_mul_f32_e32 v223, v222, v221
	v_fma_f32 v224, -v220, v223, v222
	v_fmac_f32_e32 v223, v224, v221
	v_fma_f32 v222, -v220, v223, v222
	s_nop 0
	v_div_fmas_f32 v222, v222, v221, v223
	v_div_scale_f32 v146, vcc, v135, v139, v135
	v_mul_f32_e32 v141, v146, v144
	v_fma_f32 v143, -v225, v141, v146
	v_fmac_f32_e32 v141, v143, v144
	v_fma_f32 v146, -v225, v141, v146
	v_div_fixup_f32 v134, v222, v138, v134
	v_div_fmas_f32 v146, v146, v144, v141
	s_nop 0
	v_div_fixup_f32 v135, v146, v139, v135
	v_pk_mul_f32 v[136:137], v[134:135], v[136:137]
	s_nop 0
	v_cvt_pk_bf16_f32 v93, v136, v137
	v_lshlrev_b32_e32 v132, 16, v65
	v_and_b32_e32 v133, 0xffff0000, v65
	v_lshlrev_b32_e32 v134, 16, v97
	v_and_b32_e32 v135, 0xffff0000, v97
	v_mul_f32_e32 v138, 0xbfb8aa3b, v134
	v_mul_f32_e32 v139, 0xbfb8aa3b, v135
	v_exp_f32_e32 v138, v138
	v_exp_f32_e32 v139, v139
	v_pk_fma_f32 v[136:137], v[206:207], v[154:155], v[132:133] op_sel_hi:[1,0,1] neg_lo:[0,0,1] neg_hi:[0,0,1]
	v_add_f32_e32 v138, 1.0, v138
	v_add_f32_e32 v139, 1.0, v139
	v_pk_mul_f32 v[136:137], v[126:127], v[136:137]
	v_div_scale_f32 v220, s[4:5], v138, v138, v134
	v_div_scale_f32 v225, s[4:5], v139, v139, v135
	v_rcp_f32_e32 v221, v220
	v_rcp_f32_e32 v144, v225
	s_nop 0
	v_fma_f32 v222, -v220, v221, 1.0
	v_fma_f32 v146, -v225, v144, 1.0
	v_fmac_f32_e32 v221, v222, v221
	v_fmac_f32_e32 v144, v146, v144
	v_div_scale_f32 v222, vcc, v134, v138, v134
	v_mul_f32_e32 v223, v222, v221
	v_fma_f32 v224, -v220, v223, v222
	v_fmac_f32_e32 v223, v224, v221
	v_fma_f32 v222, -v220, v223, v222
	s_nop 0
	v_div_fmas_f32 v222, v222, v221, v223
	v_div_scale_f32 v146, vcc, v135, v139, v135
	v_mul_f32_e32 v141, v146, v144
	v_fma_f32 v143, -v225, v141, v146
	v_fmac_f32_e32 v141, v143, v144
	v_fma_f32 v146, -v225, v141, v146
	v_div_fixup_f32 v134, v222, v138, v134
	v_div_fmas_f32 v146, v146, v144, v141
	s_nop 0
	v_div_fixup_f32 v135, v146, v139, v135
	v_pk_mul_f32 v[136:137], v[134:135], v[136:137]
	s_nop 0
	v_cvt_pk_bf16_f32 v97, v136, v137
	v_lshlrev_b32_e32 v132, 16, v69
	v_and_b32_e32 v133, 0xffff0000, v69
	v_lshlrev_b32_e32 v134, 16, v101
	v_and_b32_e32 v135, 0xffff0000, v101
	v_mul_f32_e32 v138, 0xbfb8aa3b, v134
	v_mul_f32_e32 v139, 0xbfb8aa3b, v135
	v_exp_f32_e32 v138, v138
	v_exp_f32_e32 v139, v139
	v_pk_fma_f32 v[136:137], v[208:209], v[156:157], v[132:133] op_sel_hi:[1,0,1] neg_lo:[0,0,1] neg_hi:[0,0,1]
	v_add_f32_e32 v138, 1.0, v138
	v_add_f32_e32 v139, 1.0, v139
	v_pk_mul_f32 v[136:137], v[126:127], v[136:137]
	v_div_scale_f32 v220, s[4:5], v138, v138, v134
	v_div_scale_f32 v225, s[4:5], v139, v139, v135
	v_rcp_f32_e32 v221, v220
	v_rcp_f32_e32 v144, v225
	s_nop 0
	v_fma_f32 v222, -v220, v221, 1.0
	v_fma_f32 v146, -v225, v144, 1.0
	v_fmac_f32_e32 v221, v222, v221
	v_fmac_f32_e32 v144, v146, v144
	v_div_scale_f32 v222, vcc, v134, v138, v134
	v_mul_f32_e32 v223, v222, v221
	v_fma_f32 v224, -v220, v223, v222
	v_fmac_f32_e32 v223, v224, v221
	v_fma_f32 v222, -v220, v223, v222
	s_nop 0
	v_div_fmas_f32 v222, v222, v221, v223
	v_div_scale_f32 v146, vcc, v135, v139, v135
	v_mul_f32_e32 v141, v146, v144
	v_fma_f32 v143, -v225, v141, v146
	v_fmac_f32_e32 v141, v143, v144
	v_fma_f32 v146, -v225, v141, v146
	v_div_fixup_f32 v134, v222, v138, v134
	v_div_fmas_f32 v146, v146, v144, v141
	s_nop 0
	v_div_fixup_f32 v135, v146, v139, v135
	v_pk_mul_f32 v[136:137], v[134:135], v[136:137]
	s_nop 0
	v_cvt_pk_bf16_f32 v101, v136, v137
	v_lshlrev_b32_e32 v132, 16, v73
	v_and_b32_e32 v133, 0xffff0000, v73
	v_lshlrev_b32_e32 v134, 16, v105
	v_and_b32_e32 v135, 0xffff0000, v105
	v_mul_f32_e32 v138, 0xbfb8aa3b, v134
	v_mul_f32_e32 v139, 0xbfb8aa3b, v135
	v_exp_f32_e32 v138, v138
	v_exp_f32_e32 v139, v139
	v_pk_fma_f32 v[136:137], v[210:211], v[158:159], v[132:133] op_sel_hi:[1,0,1] neg_lo:[0,0,1] neg_hi:[0,0,1]
	v_add_f32_e32 v138, 1.0, v138
	v_add_f32_e32 v139, 1.0, v139
	v_pk_mul_f32 v[136:137], v[126:127], v[136:137]
	v_div_scale_f32 v220, s[4:5], v138, v138, v134
	v_div_scale_f32 v225, s[4:5], v139, v139, v135
	v_rcp_f32_e32 v221, v220
	v_rcp_f32_e32 v144, v225
	s_nop 0
	v_fma_f32 v222, -v220, v221, 1.0
	v_fma_f32 v146, -v225, v144, 1.0
	v_fmac_f32_e32 v221, v222, v221
	v_fmac_f32_e32 v144, v146, v144
	v_div_scale_f32 v222, vcc, v134, v138, v134
	v_mul_f32_e32 v223, v222, v221
	v_fma_f32 v224, -v220, v223, v222
	v_fmac_f32_e32 v223, v224, v221
	v_fma_f32 v222, -v220, v223, v222
	s_nop 0
	v_div_fmas_f32 v222, v222, v221, v223
	v_div_scale_f32 v146, vcc, v135, v139, v135
	v_mul_f32_e32 v141, v146, v144
	v_fma_f32 v143, -v225, v141, v146
	v_fmac_f32_e32 v141, v143, v144
	v_fma_f32 v146, -v225, v141, v146
	v_div_fixup_f32 v134, v222, v138, v134
	v_div_fmas_f32 v146, v146, v144, v141
	s_nop 0
	v_div_fixup_f32 v135, v146, v139, v135
	v_pk_mul_f32 v[136:137], v[134:135], v[136:137]
	s_nop 0
	v_cvt_pk_bf16_f32 v105, v136, v137
	v_lshlrev_b32_e32 v132, 16, v77
	v_and_b32_e32 v133, 0xffff0000, v77
	v_lshlrev_b32_e32 v134, 16, v109
	v_and_b32_e32 v135, 0xffff0000, v109
	v_mul_f32_e32 v138, 0xbfb8aa3b, v134
	v_mul_f32_e32 v139, 0xbfb8aa3b, v135
	v_exp_f32_e32 v138, v138
	v_exp_f32_e32 v139, v139
	v_pk_fma_f32 v[136:137], v[212:213], v[160:161], v[132:133] op_sel_hi:[1,0,1] neg_lo:[0,0,1] neg_hi:[0,0,1]
	v_add_f32_e32 v138, 1.0, v138
	v_add_f32_e32 v139, 1.0, v139
	v_pk_mul_f32 v[136:137], v[126:127], v[136:137]
	v_div_scale_f32 v220, s[4:5], v138, v138, v134
	v_div_scale_f32 v225, s[4:5], v139, v139, v135
	v_rcp_f32_e32 v221, v220
	v_rcp_f32_e32 v144, v225
	s_nop 0
	v_fma_f32 v222, -v220, v221, 1.0
	v_fma_f32 v146, -v225, v144, 1.0
	v_fmac_f32_e32 v221, v222, v221
	v_fmac_f32_e32 v144, v146, v144
	v_div_scale_f32 v222, vcc, v134, v138, v134
	v_mul_f32_e32 v223, v222, v221
	v_fma_f32 v224, -v220, v223, v222
	v_fmac_f32_e32 v223, v224, v221
	v_fma_f32 v222, -v220, v223, v222
	s_nop 0
	v_div_fmas_f32 v222, v222, v221, v223
	v_div_scale_f32 v146, vcc, v135, v139, v135
	v_mul_f32_e32 v141, v146, v144
	v_fma_f32 v143, -v225, v141, v146
	v_fmac_f32_e32 v141, v143, v144
	v_fma_f32 v146, -v225, v141, v146
	v_div_fixup_f32 v134, v222, v138, v134
	v_div_fmas_f32 v146, v146, v144, v141
	s_nop 0
	v_div_fixup_f32 v135, v146, v139, v135
	v_pk_mul_f32 v[136:137], v[134:135], v[136:137]
	s_nop 0
	v_cvt_pk_bf16_f32 v109, v136, v137
	v_lshlrev_b32_e32 v132, 16, v81
	v_and_b32_e32 v133, 0xffff0000, v81
	v_lshlrev_b32_e32 v134, 16, v113
	v_and_b32_e32 v135, 0xffff0000, v113
	v_mul_f32_e32 v138, 0xbfb8aa3b, v134
	v_mul_f32_e32 v139, 0xbfb8aa3b, v135
	v_exp_f32_e32 v138, v138
	v_exp_f32_e32 v139, v139
	v_pk_fma_f32 v[136:137], v[214:215], v[162:163], v[132:133] op_sel_hi:[1,0,1] neg_lo:[0,0,1] neg_hi:[0,0,1]
	v_add_f32_e32 v138, 1.0, v138
	v_add_f32_e32 v139, 1.0, v139
	v_pk_mul_f32 v[136:137], v[126:127], v[136:137]
	v_div_scale_f32 v220, s[4:5], v138, v138, v134
	v_div_scale_f32 v225, s[4:5], v139, v139, v135
	v_rcp_f32_e32 v221, v220
	v_rcp_f32_e32 v144, v225
	s_nop 0
	v_fma_f32 v222, -v220, v221, 1.0
	v_fma_f32 v146, -v225, v144, 1.0
	v_fmac_f32_e32 v221, v222, v221
	v_fmac_f32_e32 v144, v146, v144
	v_div_scale_f32 v222, vcc, v134, v138, v134
	v_mul_f32_e32 v223, v222, v221
	v_fma_f32 v224, -v220, v223, v222
	v_fmac_f32_e32 v223, v224, v221
	v_fma_f32 v222, -v220, v223, v222
	s_nop 0
	v_div_fmas_f32 v222, v222, v221, v223
	v_div_scale_f32 v146, vcc, v135, v139, v135
	v_mul_f32_e32 v141, v146, v144
	v_fma_f32 v143, -v225, v141, v146
	v_fmac_f32_e32 v141, v143, v144
	v_fma_f32 v146, -v225, v141, v146
	v_div_fixup_f32 v134, v222, v138, v134
	v_div_fmas_f32 v146, v146, v144, v141
	s_nop 0
	v_div_fixup_f32 v135, v146, v139, v135
	v_pk_mul_f32 v[136:137], v[134:135], v[136:137]
	s_nop 0
	v_cvt_pk_bf16_f32 v113, v136, v137
	v_lshlrev_b32_e32 v132, 16, v85
	v_and_b32_e32 v133, 0xffff0000, v85
	v_lshlrev_b32_e32 v134, 16, v117
	v_and_b32_e32 v135, 0xffff0000, v117
	v_mul_f32_e32 v138, 0xbfb8aa3b, v134
	v_mul_f32_e32 v139, 0xbfb8aa3b, v135
	v_exp_f32_e32 v138, v138
	v_exp_f32_e32 v139, v139
	v_pk_fma_f32 v[136:137], v[216:217], v[164:165], v[132:133] op_sel_hi:[1,0,1] neg_lo:[0,0,1] neg_hi:[0,0,1]
	v_add_f32_e32 v138, 1.0, v138
	v_add_f32_e32 v139, 1.0, v139
	v_pk_mul_f32 v[136:137], v[126:127], v[136:137]
	v_div_scale_f32 v220, s[4:5], v138, v138, v134
	v_div_scale_f32 v225, s[4:5], v139, v139, v135
	v_rcp_f32_e32 v221, v220
	v_rcp_f32_e32 v144, v225
	s_nop 0
	v_fma_f32 v222, -v220, v221, 1.0
	v_fma_f32 v146, -v225, v144, 1.0
	v_fmac_f32_e32 v221, v222, v221
	v_fmac_f32_e32 v144, v146, v144
	v_div_scale_f32 v222, vcc, v134, v138, v134
	v_mul_f32_e32 v223, v222, v221
	v_fma_f32 v224, -v220, v223, v222
	v_fmac_f32_e32 v223, v224, v221
	v_fma_f32 v222, -v220, v223, v222
	s_nop 0
	v_div_fmas_f32 v222, v222, v221, v223
	v_div_scale_f32 v146, vcc, v135, v139, v135
	v_mul_f32_e32 v141, v146, v144
	v_fma_f32 v143, -v225, v141, v146
	v_fmac_f32_e32 v141, v143, v144
	v_fma_f32 v146, -v225, v141, v146
	v_div_fixup_f32 v134, v222, v138, v134
	v_div_fmas_f32 v146, v146, v144, v141
	s_nop 0
	v_div_fixup_f32 v135, v146, v139, v135
	v_pk_mul_f32 v[136:137], v[134:135], v[136:137]
	s_nop 0
	v_cvt_pk_bf16_f32 v117, v136, v137
	v_lshlrev_b32_e32 v132, 16, v89
	v_and_b32_e32 v133, 0xffff0000, v89
	v_lshlrev_b32_e32 v134, 16, v121
	v_and_b32_e32 v135, 0xffff0000, v121
	v_mul_f32_e32 v138, 0xbfb8aa3b, v134
	v_mul_f32_e32 v139, 0xbfb8aa3b, v135
	v_exp_f32_e32 v138, v138
	v_exp_f32_e32 v139, v139
	v_pk_fma_f32 v[136:137], v[218:219], v[166:167], v[132:133] op_sel_hi:[1,0,1] neg_lo:[0,0,1] neg_hi:[0,0,1]
	v_add_f32_e32 v138, 1.0, v138
	v_add_f32_e32 v139, 1.0, v139
	v_pk_mul_f32 v[136:137], v[126:127], v[136:137]
	v_div_scale_f32 v220, s[4:5], v138, v138, v134
	v_div_scale_f32 v225, s[4:5], v139, v139, v135
	v_rcp_f32_e32 v221, v220
	v_rcp_f32_e32 v144, v225
	s_nop 0
	v_fma_f32 v222, -v220, v221, 1.0
	v_fma_f32 v146, -v225, v144, 1.0
	v_fmac_f32_e32 v221, v222, v221
	v_fmac_f32_e32 v144, v146, v144
	v_div_scale_f32 v222, vcc, v134, v138, v134
	v_mul_f32_e32 v223, v222, v221
	v_fma_f32 v224, -v220, v223, v222
	v_fmac_f32_e32 v223, v224, v221
	v_fma_f32 v222, -v220, v223, v222
	s_nop 0
	v_div_fmas_f32 v222, v222, v221, v223
	v_div_scale_f32 v146, vcc, v135, v139, v135
	v_mul_f32_e32 v141, v146, v144
	v_fma_f32 v143, -v225, v141, v146
	v_fmac_f32_e32 v141, v143, v144
	v_fma_f32 v146, -v225, v141, v146
	v_div_fixup_f32 v134, v222, v138, v134
	v_div_fmas_f32 v146, v146, v144, v141
	s_nop 0
	v_div_fixup_f32 v135, v146, v139, v135
	v_pk_mul_f32 v[136:137], v[134:135], v[136:137]
	s_nop 0
	v_cvt_pk_bf16_f32 v121, v136, v137
	v_lshlrev_b32_e32 v174, 16, v2
	v_and_b32_e32 v175, 0xffff0000, v2
	v_lshlrev_b32_e32 v176, 16, v6
	v_and_b32_e32 v177, 0xffff0000, v6
	v_lshlrev_b32_e32 v178, 16, v10
	v_and_b32_e32 v179, 0xffff0000, v10
	v_lshlrev_b32_e32 v180, 16, v14
	v_and_b32_e32 v181, 0xffff0000, v14
	v_lshlrev_b32_e32 v182, 16, v18
	v_and_b32_e32 v183, 0xffff0000, v18
	v_lshlrev_b32_e32 v184, 16, v22
	v_and_b32_e32 v185, 0xffff0000, v22
	v_lshlrev_b32_e32 v186, 16, v26
	v_and_b32_e32 v187, 0xffff0000, v26
	v_lshlrev_b32_e32 v188, 16, v30
	v_and_b32_e32 v189, 0xffff0000, v30
	v_lshlrev_b32_e32 v190, 16, v34
	v_and_b32_e32 v191, 0xffff0000, v34
	v_lshlrev_b32_e32 v192, 16, v38
	v_and_b32_e32 v193, 0xffff0000, v38
	v_lshlrev_b32_e32 v194, 16, v42
	v_and_b32_e32 v195, 0xffff0000, v42
	v_lshlrev_b32_e32 v196, 16, v46
	v_and_b32_e32 v197, 0xffff0000, v46
	v_lshlrev_b32_e32 v198, 16, v50
	v_and_b32_e32 v199, 0xffff0000, v50
	v_lshlrev_b32_e32 v200, 16, v54
	v_and_b32_e32 v201, 0xffff0000, v54
	v_lshlrev_b32_e32 v202, 16, v58
	v_and_b32_e32 v203, 0xffff0000, v58
	v_lshlrev_b32_e32 v204, 16, v62
	v_and_b32_e32 v205, 0xffff0000, v62
	v_lshlrev_b32_e32 v206, 16, v66
	v_and_b32_e32 v207, 0xffff0000, v66
	v_lshlrev_b32_e32 v208, 16, v70
	v_and_b32_e32 v209, 0xffff0000, v70
	v_lshlrev_b32_e32 v210, 16, v74
	v_and_b32_e32 v211, 0xffff0000, v74
	v_lshlrev_b32_e32 v212, 16, v78
	v_and_b32_e32 v213, 0xffff0000, v78
	v_lshlrev_b32_e32 v214, 16, v82
	v_and_b32_e32 v215, 0xffff0000, v82
	v_lshlrev_b32_e32 v216, 16, v86
	v_and_b32_e32 v217, 0xffff0000, v86
	v_lshlrev_b32_e32 v218, 16, v90
	v_and_b32_e32 v219, 0xffff0000, v90
	v_pk_add_f32 v[218:219], v[218:219], v[216:217]
	v_pk_add_f32 v[216:217], v[216:217], v[214:215]
	v_pk_add_f32 v[214:215], v[214:215], v[212:213]
	v_pk_add_f32 v[212:213], v[212:213], v[210:211]
	v_pk_add_f32 v[210:211], v[210:211], v[208:209]
	v_pk_add_f32 v[208:209], v[208:209], v[206:207]
	v_pk_add_f32 v[206:207], v[206:207], v[204:205]
	v_pk_add_f32 v[204:205], v[204:205], v[202:203]
	v_pk_add_f32 v[202:203], v[202:203], v[200:201]
	v_pk_add_f32 v[200:201], v[200:201], v[198:199]
	v_pk_add_f32 v[198:199], v[198:199], v[196:197]
	v_pk_add_f32 v[196:197], v[196:197], v[194:195]
	v_pk_add_f32 v[194:195], v[194:195], v[192:193]
	v_pk_add_f32 v[192:193], v[192:193], v[190:191]
	v_pk_add_f32 v[190:191], v[190:191], v[188:189]
	v_pk_add_f32 v[188:189], v[188:189], v[186:187]
	v_pk_add_f32 v[186:187], v[186:187], v[184:185]
	v_pk_add_f32 v[184:185], v[184:185], v[182:183]
	v_pk_add_f32 v[182:183], v[182:183], v[180:181]
	v_pk_add_f32 v[180:181], v[180:181], v[178:179]
	v_pk_add_f32 v[178:179], v[178:179], v[176:177]
	v_pk_add_f32 v[176:177], v[176:177], v[174:175]
	v_pk_fma_f32 v[218:219], v[214:215], v[168:169], v[218:219] op_sel_hi:[1,0,1]
	v_pk_fma_f32 v[216:217], v[212:213], v[168:169], v[216:217] op_sel_hi:[1,0,1]
	v_pk_fma_f32 v[214:215], v[210:211], v[168:169], v[214:215] op_sel_hi:[1,0,1]
	v_pk_fma_f32 v[212:213], v[208:209], v[168:169], v[212:213] op_sel_hi:[1,0,1]
	v_pk_fma_f32 v[210:211], v[206:207], v[168:169], v[210:211] op_sel_hi:[1,0,1]
	v_pk_fma_f32 v[208:209], v[204:205], v[168:169], v[208:209] op_sel_hi:[1,0,1]
	v_pk_fma_f32 v[206:207], v[202:203], v[168:169], v[206:207] op_sel_hi:[1,0,1]
	v_pk_fma_f32 v[204:205], v[200:201], v[168:169], v[204:205] op_sel_hi:[1,0,1]
	v_pk_fma_f32 v[202:203], v[198:199], v[168:169], v[202:203] op_sel_hi:[1,0,1]
	v_pk_fma_f32 v[200:201], v[196:197], v[168:169], v[200:201] op_sel_hi:[1,0,1]
	v_pk_fma_f32 v[198:199], v[194:195], v[168:169], v[198:199] op_sel_hi:[1,0,1]
	v_pk_fma_f32 v[196:197], v[192:193], v[168:169], v[196:197] op_sel_hi:[1,0,1]
	v_pk_fma_f32 v[194:195], v[190:191], v[168:169], v[194:195] op_sel_hi:[1,0,1]
	v_pk_fma_f32 v[192:193], v[188:189], v[168:169], v[192:193] op_sel_hi:[1,0,1]
	v_pk_fma_f32 v[190:191], v[186:187], v[168:169], v[190:191] op_sel_hi:[1,0,1]
	v_pk_fma_f32 v[188:189], v[184:185], v[168:169], v[188:189] op_sel_hi:[1,0,1]
	v_pk_fma_f32 v[186:187], v[182:183], v[168:169], v[186:187] op_sel_hi:[1,0,1]
	v_pk_fma_f32 v[184:185], v[180:181], v[168:169], v[184:185] op_sel_hi:[1,0,1]
	v_pk_fma_f32 v[182:183], v[178:179], v[168:169], v[182:183] op_sel_hi:[1,0,1]
	v_pk_fma_f32 v[180:181], v[176:177], v[168:169], v[180:181] op_sel_hi:[1,0,1]
	v_pk_fma_f32 v[218:219], v[210:211], v[170:171], v[218:219] op_sel_hi:[1,0,1]
	v_pk_fma_f32 v[216:217], v[208:209], v[170:171], v[216:217] op_sel_hi:[1,0,1]
	v_pk_fma_f32 v[214:215], v[206:207], v[170:171], v[214:215] op_sel_hi:[1,0,1]
	v_pk_fma_f32 v[212:213], v[204:205], v[170:171], v[212:213] op_sel_hi:[1,0,1]
	v_pk_fma_f32 v[210:211], v[202:203], v[170:171], v[210:211] op_sel_hi:[1,0,1]
	v_pk_fma_f32 v[208:209], v[200:201], v[170:171], v[208:209] op_sel_hi:[1,0,1]
	v_pk_fma_f32 v[206:207], v[198:199], v[170:171], v[206:207] op_sel_hi:[1,0,1]
	v_pk_fma_f32 v[204:205], v[196:197], v[170:171], v[204:205] op_sel_hi:[1,0,1]
	v_pk_fma_f32 v[202:203], v[194:195], v[170:171], v[202:203] op_sel_hi:[1,0,1]
	v_pk_fma_f32 v[200:201], v[192:193], v[170:171], v[200:201] op_sel_hi:[1,0,1]
	v_pk_fma_f32 v[198:199], v[190:191], v[170:171], v[198:199] op_sel_hi:[1,0,1]
	v_pk_fma_f32 v[196:197], v[188:189], v[170:171], v[196:197] op_sel_hi:[1,0,1]
	v_pk_fma_f32 v[194:195], v[186:187], v[170:171], v[194:195] op_sel_hi:[1,0,1]
	v_pk_fma_f32 v[192:193], v[184:185], v[170:171], v[192:193] op_sel_hi:[1,0,1]
	v_pk_fma_f32 v[190:191], v[182:183], v[170:171], v[190:191] op_sel_hi:[1,0,1]
	v_pk_fma_f32 v[188:189], v[180:181], v[170:171], v[188:189] op_sel_hi:[1,0,1]
	v_pk_fma_f32 v[218:219], v[202:203], v[172:173], v[218:219] op_sel_hi:[1,0,1]
	v_pk_fma_f32 v[216:217], v[200:201], v[172:173], v[216:217] op_sel_hi:[1,0,1]
	v_pk_fma_f32 v[214:215], v[198:199], v[172:173], v[214:215] op_sel_hi:[1,0,1]
	v_pk_fma_f32 v[212:213], v[196:197], v[172:173], v[212:213] op_sel_hi:[1,0,1]
	v_pk_fma_f32 v[210:211], v[194:195], v[172:173], v[210:211] op_sel_hi:[1,0,1]
	v_pk_fma_f32 v[208:209], v[192:193], v[172:173], v[208:209] op_sel_hi:[1,0,1]
	v_pk_fma_f32 v[206:207], v[190:191], v[172:173], v[206:207] op_sel_hi:[1,0,1]
	v_pk_fma_f32 v[204:205], v[188:189], v[172:173], v[204:205] op_sel_hi:[1,0,1]
	v_lshlrev_b32_e32 v132, 16, v62
	v_and_b32_e32 v133, 0xffff0000, v62
	v_lshlrev_b32_e32 v134, 16, v94
	v_and_b32_e32 v135, 0xffff0000, v94
	v_mul_f32_e32 v138, 0xbfb8aa3b, v134
	v_mul_f32_e32 v139, 0xbfb8aa3b, v135
	v_exp_f32_e32 v138, v138
	v_exp_f32_e32 v139, v139
	v_pk_fma_f32 v[136:137], v[204:205], v[152:153], v[132:133] op_sel_hi:[1,0,1] neg_lo:[0,0,1] neg_hi:[0,0,1]
	v_add_f32_e32 v138, 1.0, v138
	v_add_f32_e32 v139, 1.0, v139
	v_pk_mul_f32 v[136:137], v[128:129], v[136:137]
	v_div_scale_f32 v220, s[4:5], v138, v138, v134
	v_div_scale_f32 v225, s[4:5], v139, v139, v135
	v_rcp_f32_e32 v221, v220
	v_rcp_f32_e32 v144, v225
	s_nop 0
	v_fma_f32 v222, -v220, v221, 1.0
	v_fma_f32 v146, -v225, v144, 1.0
	v_fmac_f32_e32 v221, v222, v221
	v_fmac_f32_e32 v144, v146, v144
	v_div_scale_f32 v222, vcc, v134, v138, v134
	v_mul_f32_e32 v223, v222, v221
	v_fma_f32 v224, -v220, v223, v222
	v_fmac_f32_e32 v223, v224, v221
	v_fma_f32 v222, -v220, v223, v222
	s_nop 0
	v_div_fmas_f32 v222, v222, v221, v223
	v_div_scale_f32 v146, vcc, v135, v139, v135
	v_mul_f32_e32 v141, v146, v144
	v_fma_f32 v143, -v225, v141, v146
	v_fmac_f32_e32 v141, v143, v144
	v_fma_f32 v146, -v225, v141, v146
	v_div_fixup_f32 v134, v222, v138, v134
	v_div_fmas_f32 v146, v146, v144, v141
	s_nop 0
	v_div_fixup_f32 v135, v146, v139, v135
	v_pk_mul_f32 v[136:137], v[134:135], v[136:137]
	s_nop 0
	v_cvt_pk_bf16_f32 v94, v136, v137
	v_lshlrev_b32_e32 v132, 16, v66
	v_and_b32_e32 v133, 0xffff0000, v66
	v_lshlrev_b32_e32 v134, 16, v98
	v_and_b32_e32 v135, 0xffff0000, v98
	v_mul_f32_e32 v138, 0xbfb8aa3b, v134
	v_mul_f32_e32 v139, 0xbfb8aa3b, v135
	v_exp_f32_e32 v138, v138
	v_exp_f32_e32 v139, v139
	v_pk_fma_f32 v[136:137], v[206:207], v[154:155], v[132:133] op_sel_hi:[1,0,1] neg_lo:[0,0,1] neg_hi:[0,0,1]
	v_add_f32_e32 v138, 1.0, v138
	v_add_f32_e32 v139, 1.0, v139
	v_pk_mul_f32 v[136:137], v[128:129], v[136:137]
	v_div_scale_f32 v220, s[4:5], v138, v138, v134
	v_div_scale_f32 v225, s[4:5], v139, v139, v135
	v_rcp_f32_e32 v221, v220
	v_rcp_f32_e32 v144, v225
	s_nop 0
	v_fma_f32 v222, -v220, v221, 1.0
	v_fma_f32 v146, -v225, v144, 1.0
	v_fmac_f32_e32 v221, v222, v221
	v_fmac_f32_e32 v144, v146, v144
	v_div_scale_f32 v222, vcc, v134, v138, v134
	v_mul_f32_e32 v223, v222, v221
	v_fma_f32 v224, -v220, v223, v222
	v_fmac_f32_e32 v223, v224, v221
	v_fma_f32 v222, -v220, v223, v222
	s_nop 0
	v_div_fmas_f32 v222, v222, v221, v223
	v_div_scale_f32 v146, vcc, v135, v139, v135
	v_mul_f32_e32 v141, v146, v144
	v_fma_f32 v143, -v225, v141, v146
	v_fmac_f32_e32 v141, v143, v144
	v_fma_f32 v146, -v225, v141, v146
	v_div_fixup_f32 v134, v222, v138, v134
	v_div_fmas_f32 v146, v146, v144, v141
	s_nop 0
	v_div_fixup_f32 v135, v146, v139, v135
	v_pk_mul_f32 v[136:137], v[134:135], v[136:137]
	s_nop 0
	v_cvt_pk_bf16_f32 v98, v136, v137
	v_lshlrev_b32_e32 v132, 16, v70
	v_and_b32_e32 v133, 0xffff0000, v70
	v_lshlrev_b32_e32 v134, 16, v102
	v_and_b32_e32 v135, 0xffff0000, v102
	v_mul_f32_e32 v138, 0xbfb8aa3b, v134
	v_mul_f32_e32 v139, 0xbfb8aa3b, v135
	v_exp_f32_e32 v138, v138
	v_exp_f32_e32 v139, v139
	v_pk_fma_f32 v[136:137], v[208:209], v[156:157], v[132:133] op_sel_hi:[1,0,1] neg_lo:[0,0,1] neg_hi:[0,0,1]
	v_add_f32_e32 v138, 1.0, v138
	v_add_f32_e32 v139, 1.0, v139
	v_pk_mul_f32 v[136:137], v[128:129], v[136:137]
	v_div_scale_f32 v220, s[4:5], v138, v138, v134
	v_div_scale_f32 v225, s[4:5], v139, v139, v135
	v_rcp_f32_e32 v221, v220
	v_rcp_f32_e32 v144, v225
	s_nop 0
	v_fma_f32 v222, -v220, v221, 1.0
	v_fma_f32 v146, -v225, v144, 1.0
	v_fmac_f32_e32 v221, v222, v221
	v_fmac_f32_e32 v144, v146, v144
	v_div_scale_f32 v222, vcc, v134, v138, v134
	v_mul_f32_e32 v223, v222, v221
	v_fma_f32 v224, -v220, v223, v222
	v_fmac_f32_e32 v223, v224, v221
	v_fma_f32 v222, -v220, v223, v222
	s_nop 0
	v_div_fmas_f32 v222, v222, v221, v223
	v_div_scale_f32 v146, vcc, v135, v139, v135
	v_mul_f32_e32 v141, v146, v144
	v_fma_f32 v143, -v225, v141, v146
	v_fmac_f32_e32 v141, v143, v144
	v_fma_f32 v146, -v225, v141, v146
	v_div_fixup_f32 v134, v222, v138, v134
	v_div_fmas_f32 v146, v146, v144, v141
	s_nop 0
	v_div_fixup_f32 v135, v146, v139, v135
	v_pk_mul_f32 v[136:137], v[134:135], v[136:137]
	s_nop 0
	v_cvt_pk_bf16_f32 v102, v136, v137
	v_lshlrev_b32_e32 v132, 16, v74
	v_and_b32_e32 v133, 0xffff0000, v74
	v_lshlrev_b32_e32 v134, 16, v106
	v_and_b32_e32 v135, 0xffff0000, v106
	v_mul_f32_e32 v138, 0xbfb8aa3b, v134
	v_mul_f32_e32 v139, 0xbfb8aa3b, v135
	v_exp_f32_e32 v138, v138
	v_exp_f32_e32 v139, v139
	v_pk_fma_f32 v[136:137], v[210:211], v[158:159], v[132:133] op_sel_hi:[1,0,1] neg_lo:[0,0,1] neg_hi:[0,0,1]
	v_add_f32_e32 v138, 1.0, v138
	v_add_f32_e32 v139, 1.0, v139
	v_pk_mul_f32 v[136:137], v[128:129], v[136:137]
	v_div_scale_f32 v220, s[4:5], v138, v138, v134
	v_div_scale_f32 v225, s[4:5], v139, v139, v135
	v_rcp_f32_e32 v221, v220
	v_rcp_f32_e32 v144, v225
	s_nop 0
	v_fma_f32 v222, -v220, v221, 1.0
	v_fma_f32 v146, -v225, v144, 1.0
	v_fmac_f32_e32 v221, v222, v221
	v_fmac_f32_e32 v144, v146, v144
	v_div_scale_f32 v222, vcc, v134, v138, v134
	v_mul_f32_e32 v223, v222, v221
	v_fma_f32 v224, -v220, v223, v222
	v_fmac_f32_e32 v223, v224, v221
	v_fma_f32 v222, -v220, v223, v222
	s_nop 0
	v_div_fmas_f32 v222, v222, v221, v223
	v_div_scale_f32 v146, vcc, v135, v139, v135
	v_mul_f32_e32 v141, v146, v144
	v_fma_f32 v143, -v225, v141, v146
	v_fmac_f32_e32 v141, v143, v144
	v_fma_f32 v146, -v225, v141, v146
	v_div_fixup_f32 v134, v222, v138, v134
	v_div_fmas_f32 v146, v146, v144, v141
	s_nop 0
	v_div_fixup_f32 v135, v146, v139, v135
	v_pk_mul_f32 v[136:137], v[134:135], v[136:137]
	s_nop 0
	v_cvt_pk_bf16_f32 v106, v136, v137
	v_lshlrev_b32_e32 v132, 16, v78
	v_and_b32_e32 v133, 0xffff0000, v78
	v_lshlrev_b32_e32 v134, 16, v110
	v_and_b32_e32 v135, 0xffff0000, v110
	v_mul_f32_e32 v138, 0xbfb8aa3b, v134
	v_mul_f32_e32 v139, 0xbfb8aa3b, v135
	v_exp_f32_e32 v138, v138
	v_exp_f32_e32 v139, v139
	v_pk_fma_f32 v[136:137], v[212:213], v[160:161], v[132:133] op_sel_hi:[1,0,1] neg_lo:[0,0,1] neg_hi:[0,0,1]
	v_add_f32_e32 v138, 1.0, v138
	v_add_f32_e32 v139, 1.0, v139
	v_pk_mul_f32 v[136:137], v[128:129], v[136:137]
	v_div_scale_f32 v220, s[4:5], v138, v138, v134
	v_div_scale_f32 v225, s[4:5], v139, v139, v135
	v_rcp_f32_e32 v221, v220
	v_rcp_f32_e32 v144, v225
	s_nop 0
	v_fma_f32 v222, -v220, v221, 1.0
	v_fma_f32 v146, -v225, v144, 1.0
	v_fmac_f32_e32 v221, v222, v221
	v_fmac_f32_e32 v144, v146, v144
	v_div_scale_f32 v222, vcc, v134, v138, v134
	v_mul_f32_e32 v223, v222, v221
	v_fma_f32 v224, -v220, v223, v222
	v_fmac_f32_e32 v223, v224, v221
	v_fma_f32 v222, -v220, v223, v222
	s_nop 0
	v_div_fmas_f32 v222, v222, v221, v223
	v_div_scale_f32 v146, vcc, v135, v139, v135
	v_mul_f32_e32 v141, v146, v144
	v_fma_f32 v143, -v225, v141, v146
	v_fmac_f32_e32 v141, v143, v144
	v_fma_f32 v146, -v225, v141, v146
	v_div_fixup_f32 v134, v222, v138, v134
	v_div_fmas_f32 v146, v146, v144, v141
	s_nop 0
	v_div_fixup_f32 v135, v146, v139, v135
	v_pk_mul_f32 v[136:137], v[134:135], v[136:137]
	s_nop 0
	v_cvt_pk_bf16_f32 v110, v136, v137
	v_lshlrev_b32_e32 v132, 16, v82
	v_and_b32_e32 v133, 0xffff0000, v82
	v_lshlrev_b32_e32 v134, 16, v114
	v_and_b32_e32 v135, 0xffff0000, v114
	v_mul_f32_e32 v138, 0xbfb8aa3b, v134
	v_mul_f32_e32 v139, 0xbfb8aa3b, v135
	v_exp_f32_e32 v138, v138
	v_exp_f32_e32 v139, v139
	v_pk_fma_f32 v[136:137], v[214:215], v[162:163], v[132:133] op_sel_hi:[1,0,1] neg_lo:[0,0,1] neg_hi:[0,0,1]
	v_add_f32_e32 v138, 1.0, v138
	v_add_f32_e32 v139, 1.0, v139
	v_pk_mul_f32 v[136:137], v[128:129], v[136:137]
	v_div_scale_f32 v220, s[4:5], v138, v138, v134
	v_div_scale_f32 v225, s[4:5], v139, v139, v135
	v_rcp_f32_e32 v221, v220
	v_rcp_f32_e32 v144, v225
	s_nop 0
	v_fma_f32 v222, -v220, v221, 1.0
	v_fma_f32 v146, -v225, v144, 1.0
	v_fmac_f32_e32 v221, v222, v221
	v_fmac_f32_e32 v144, v146, v144
	v_div_scale_f32 v222, vcc, v134, v138, v134
	v_mul_f32_e32 v223, v222, v221
	v_fma_f32 v224, -v220, v223, v222
	v_fmac_f32_e32 v223, v224, v221
	v_fma_f32 v222, -v220, v223, v222
	s_nop 0
	v_div_fmas_f32 v222, v222, v221, v223
	v_div_scale_f32 v146, vcc, v135, v139, v135
	v_mul_f32_e32 v141, v146, v144
	v_fma_f32 v143, -v225, v141, v146
	v_fmac_f32_e32 v141, v143, v144
	v_fma_f32 v146, -v225, v141, v146
	v_div_fixup_f32 v134, v222, v138, v134
	v_div_fmas_f32 v146, v146, v144, v141
	s_nop 0
	v_div_fixup_f32 v135, v146, v139, v135
	v_pk_mul_f32 v[136:137], v[134:135], v[136:137]
	s_nop 0
	v_cvt_pk_bf16_f32 v114, v136, v137
	v_lshlrev_b32_e32 v132, 16, v86
	v_and_b32_e32 v133, 0xffff0000, v86
	v_lshlrev_b32_e32 v134, 16, v118
	v_and_b32_e32 v135, 0xffff0000, v118
	v_mul_f32_e32 v138, 0xbfb8aa3b, v134
	v_mul_f32_e32 v139, 0xbfb8aa3b, v135
	v_exp_f32_e32 v138, v138
	v_exp_f32_e32 v139, v139
	v_pk_fma_f32 v[136:137], v[216:217], v[164:165], v[132:133] op_sel_hi:[1,0,1] neg_lo:[0,0,1] neg_hi:[0,0,1]
	v_add_f32_e32 v138, 1.0, v138
	v_add_f32_e32 v139, 1.0, v139
	v_pk_mul_f32 v[136:137], v[128:129], v[136:137]
	v_div_scale_f32 v220, s[4:5], v138, v138, v134
	v_div_scale_f32 v225, s[4:5], v139, v139, v135
	v_rcp_f32_e32 v221, v220
	v_rcp_f32_e32 v144, v225
	s_nop 0
	v_fma_f32 v222, -v220, v221, 1.0
	v_fma_f32 v146, -v225, v144, 1.0
	v_fmac_f32_e32 v221, v222, v221
	v_fmac_f32_e32 v144, v146, v144
	v_div_scale_f32 v222, vcc, v134, v138, v134
	v_mul_f32_e32 v223, v222, v221
	v_fma_f32 v224, -v220, v223, v222
	v_fmac_f32_e32 v223, v224, v221
	v_fma_f32 v222, -v220, v223, v222
	s_nop 0
	v_div_fmas_f32 v222, v222, v221, v223
	v_div_scale_f32 v146, vcc, v135, v139, v135
	v_mul_f32_e32 v141, v146, v144
	v_fma_f32 v143, -v225, v141, v146
	v_fmac_f32_e32 v141, v143, v144
	v_fma_f32 v146, -v225, v141, v146
	v_div_fixup_f32 v134, v222, v138, v134
	v_div_fmas_f32 v146, v146, v144, v141
	s_nop 0
	v_div_fixup_f32 v135, v146, v139, v135
	v_pk_mul_f32 v[136:137], v[134:135], v[136:137]
	s_nop 0
	v_cvt_pk_bf16_f32 v118, v136, v137
	v_lshlrev_b32_e32 v132, 16, v90
	v_and_b32_e32 v133, 0xffff0000, v90
	v_lshlrev_b32_e32 v134, 16, v122
	v_and_b32_e32 v135, 0xffff0000, v122
	v_mul_f32_e32 v138, 0xbfb8aa3b, v134
	v_mul_f32_e32 v139, 0xbfb8aa3b, v135
	v_exp_f32_e32 v138, v138
	v_exp_f32_e32 v139, v139
	v_pk_fma_f32 v[136:137], v[218:219], v[166:167], v[132:133] op_sel_hi:[1,0,1] neg_lo:[0,0,1] neg_hi:[0,0,1]
	v_add_f32_e32 v138, 1.0, v138
	v_add_f32_e32 v139, 1.0, v139
	v_pk_mul_f32 v[136:137], v[128:129], v[136:137]
	v_div_scale_f32 v220, s[4:5], v138, v138, v134
	v_div_scale_f32 v225, s[4:5], v139, v139, v135
	v_rcp_f32_e32 v221, v220
	v_rcp_f32_e32 v144, v225
	s_nop 0
	v_fma_f32 v222, -v220, v221, 1.0
	v_fma_f32 v146, -v225, v144, 1.0
	v_fmac_f32_e32 v221, v222, v221
	v_fmac_f32_e32 v144, v146, v144
	v_div_scale_f32 v222, vcc, v134, v138, v134
	v_mul_f32_e32 v223, v222, v221
	v_fma_f32 v224, -v220, v223, v222
	v_fmac_f32_e32 v223, v224, v221
	v_fma_f32 v222, -v220, v223, v222
	s_nop 0
	v_div_fmas_f32 v222, v222, v221, v223
	v_div_scale_f32 v146, vcc, v135, v139, v135
	v_mul_f32_e32 v141, v146, v144
	v_fma_f32 v143, -v225, v141, v146
	v_fmac_f32_e32 v141, v143, v144
	v_fma_f32 v146, -v225, v141, v146
	v_div_fixup_f32 v134, v222, v138, v134
	v_div_fmas_f32 v146, v146, v144, v141
	s_nop 0
	v_div_fixup_f32 v135, v146, v139, v135
	v_pk_mul_f32 v[136:137], v[134:135], v[136:137]
	s_nop 0
	v_cvt_pk_bf16_f32 v122, v136, v137
	v_lshlrev_b32_e32 v174, 16, v3
	v_and_b32_e32 v175, 0xffff0000, v3
	v_lshlrev_b32_e32 v176, 16, v7
	v_and_b32_e32 v177, 0xffff0000, v7
	v_lshlrev_b32_e32 v178, 16, v11
	v_and_b32_e32 v179, 0xffff0000, v11
	v_lshlrev_b32_e32 v180, 16, v15
	v_and_b32_e32 v181, 0xffff0000, v15
	v_lshlrev_b32_e32 v182, 16, v19
	v_and_b32_e32 v183, 0xffff0000, v19
	v_lshlrev_b32_e32 v184, 16, v23
	v_and_b32_e32 v185, 0xffff0000, v23
	v_lshlrev_b32_e32 v186, 16, v27
	v_and_b32_e32 v187, 0xffff0000, v27
	v_lshlrev_b32_e32 v188, 16, v31
	v_and_b32_e32 v189, 0xffff0000, v31
	v_lshlrev_b32_e32 v190, 16, v35
	v_and_b32_e32 v191, 0xffff0000, v35
	v_lshlrev_b32_e32 v192, 16, v39
	v_and_b32_e32 v193, 0xffff0000, v39
	v_lshlrev_b32_e32 v194, 16, v43
	v_and_b32_e32 v195, 0xffff0000, v43
	v_lshlrev_b32_e32 v196, 16, v47
	v_and_b32_e32 v197, 0xffff0000, v47
	v_lshlrev_b32_e32 v198, 16, v51
	v_and_b32_e32 v199, 0xffff0000, v51
	v_lshlrev_b32_e32 v200, 16, v55
	v_and_b32_e32 v201, 0xffff0000, v55
	v_lshlrev_b32_e32 v202, 16, v59
	v_and_b32_e32 v203, 0xffff0000, v59
	v_lshlrev_b32_e32 v204, 16, v63
	v_and_b32_e32 v205, 0xffff0000, v63
	v_lshlrev_b32_e32 v206, 16, v67
	v_and_b32_e32 v207, 0xffff0000, v67
	v_lshlrev_b32_e32 v208, 16, v71
	v_and_b32_e32 v209, 0xffff0000, v71
	v_lshlrev_b32_e32 v210, 16, v75
	v_and_b32_e32 v211, 0xffff0000, v75
	v_lshlrev_b32_e32 v212, 16, v79
	v_and_b32_e32 v213, 0xffff0000, v79
	v_lshlrev_b32_e32 v214, 16, v83
	v_and_b32_e32 v215, 0xffff0000, v83
	v_lshlrev_b32_e32 v216, 16, v87
	v_and_b32_e32 v217, 0xffff0000, v87
	v_lshlrev_b32_e32 v218, 16, v91
	v_and_b32_e32 v219, 0xffff0000, v91
	v_pk_add_f32 v[218:219], v[218:219], v[216:217]
	v_pk_add_f32 v[216:217], v[216:217], v[214:215]
	v_pk_add_f32 v[214:215], v[214:215], v[212:213]
	v_pk_add_f32 v[212:213], v[212:213], v[210:211]
	v_pk_add_f32 v[210:211], v[210:211], v[208:209]
	v_pk_add_f32 v[208:209], v[208:209], v[206:207]
	v_pk_add_f32 v[206:207], v[206:207], v[204:205]
	v_pk_add_f32 v[204:205], v[204:205], v[202:203]
	v_pk_add_f32 v[202:203], v[202:203], v[200:201]
	v_pk_add_f32 v[200:201], v[200:201], v[198:199]
	v_pk_add_f32 v[198:199], v[198:199], v[196:197]
	v_pk_add_f32 v[196:197], v[196:197], v[194:195]
	v_pk_add_f32 v[194:195], v[194:195], v[192:193]
	v_pk_add_f32 v[192:193], v[192:193], v[190:191]
	v_pk_add_f32 v[190:191], v[190:191], v[188:189]
	v_pk_add_f32 v[188:189], v[188:189], v[186:187]
	v_pk_add_f32 v[186:187], v[186:187], v[184:185]
	v_pk_add_f32 v[184:185], v[184:185], v[182:183]
	v_pk_add_f32 v[182:183], v[182:183], v[180:181]
	v_pk_add_f32 v[180:181], v[180:181], v[178:179]
	v_pk_add_f32 v[178:179], v[178:179], v[176:177]
	v_pk_add_f32 v[176:177], v[176:177], v[174:175]
	v_pk_fma_f32 v[218:219], v[214:215], v[168:169], v[218:219] op_sel_hi:[1,0,1]
	v_pk_fma_f32 v[216:217], v[212:213], v[168:169], v[216:217] op_sel_hi:[1,0,1]
	v_pk_fma_f32 v[214:215], v[210:211], v[168:169], v[214:215] op_sel_hi:[1,0,1]
	v_pk_fma_f32 v[212:213], v[208:209], v[168:169], v[212:213] op_sel_hi:[1,0,1]
	v_pk_fma_f32 v[210:211], v[206:207], v[168:169], v[210:211] op_sel_hi:[1,0,1]
	v_pk_fma_f32 v[208:209], v[204:205], v[168:169], v[208:209] op_sel_hi:[1,0,1]
	v_pk_fma_f32 v[206:207], v[202:203], v[168:169], v[206:207] op_sel_hi:[1,0,1]
	v_pk_fma_f32 v[204:205], v[200:201], v[168:169], v[204:205] op_sel_hi:[1,0,1]
	v_pk_fma_f32 v[202:203], v[198:199], v[168:169], v[202:203] op_sel_hi:[1,0,1]
	v_pk_fma_f32 v[200:201], v[196:197], v[168:169], v[200:201] op_sel_hi:[1,0,1]
	v_pk_fma_f32 v[198:199], v[194:195], v[168:169], v[198:199] op_sel_hi:[1,0,1]
	v_pk_fma_f32 v[196:197], v[192:193], v[168:169], v[196:197] op_sel_hi:[1,0,1]
	v_pk_fma_f32 v[194:195], v[190:191], v[168:169], v[194:195] op_sel_hi:[1,0,1]
	v_pk_fma_f32 v[192:193], v[188:189], v[168:169], v[192:193] op_sel_hi:[1,0,1]
	v_pk_fma_f32 v[190:191], v[186:187], v[168:169], v[190:191] op_sel_hi:[1,0,1]
	v_pk_fma_f32 v[188:189], v[184:185], v[168:169], v[188:189] op_sel_hi:[1,0,1]
	v_pk_fma_f32 v[186:187], v[182:183], v[168:169], v[186:187] op_sel_hi:[1,0,1]
	v_pk_fma_f32 v[184:185], v[180:181], v[168:169], v[184:185] op_sel_hi:[1,0,1]
	v_pk_fma_f32 v[182:183], v[178:179], v[168:169], v[182:183] op_sel_hi:[1,0,1]
	v_pk_fma_f32 v[180:181], v[176:177], v[168:169], v[180:181] op_sel_hi:[1,0,1]
	v_pk_fma_f32 v[218:219], v[210:211], v[170:171], v[218:219] op_sel_hi:[1,0,1]
	v_pk_fma_f32 v[216:217], v[208:209], v[170:171], v[216:217] op_sel_hi:[1,0,1]
	v_pk_fma_f32 v[214:215], v[206:207], v[170:171], v[214:215] op_sel_hi:[1,0,1]
	v_pk_fma_f32 v[212:213], v[204:205], v[170:171], v[212:213] op_sel_hi:[1,0,1]
	v_pk_fma_f32 v[210:211], v[202:203], v[170:171], v[210:211] op_sel_hi:[1,0,1]
	v_pk_fma_f32 v[208:209], v[200:201], v[170:171], v[208:209] op_sel_hi:[1,0,1]
	v_pk_fma_f32 v[206:207], v[198:199], v[170:171], v[206:207] op_sel_hi:[1,0,1]
	v_pk_fma_f32 v[204:205], v[196:197], v[170:171], v[204:205] op_sel_hi:[1,0,1]
	v_pk_fma_f32 v[202:203], v[194:195], v[170:171], v[202:203] op_sel_hi:[1,0,1]
	v_pk_fma_f32 v[200:201], v[192:193], v[170:171], v[200:201] op_sel_hi:[1,0,1]
	v_pk_fma_f32 v[198:199], v[190:191], v[170:171], v[198:199] op_sel_hi:[1,0,1]
	v_pk_fma_f32 v[196:197], v[188:189], v[170:171], v[196:197] op_sel_hi:[1,0,1]
	v_pk_fma_f32 v[194:195], v[186:187], v[170:171], v[194:195] op_sel_hi:[1,0,1]
	v_pk_fma_f32 v[192:193], v[184:185], v[170:171], v[192:193] op_sel_hi:[1,0,1]
	v_pk_fma_f32 v[190:191], v[182:183], v[170:171], v[190:191] op_sel_hi:[1,0,1]
	v_pk_fma_f32 v[188:189], v[180:181], v[170:171], v[188:189] op_sel_hi:[1,0,1]
	v_pk_fma_f32 v[218:219], v[202:203], v[172:173], v[218:219] op_sel_hi:[1,0,1]
	v_pk_fma_f32 v[216:217], v[200:201], v[172:173], v[216:217] op_sel_hi:[1,0,1]
	v_pk_fma_f32 v[214:215], v[198:199], v[172:173], v[214:215] op_sel_hi:[1,0,1]
	v_pk_fma_f32 v[212:213], v[196:197], v[172:173], v[212:213] op_sel_hi:[1,0,1]
	v_pk_fma_f32 v[210:211], v[194:195], v[172:173], v[210:211] op_sel_hi:[1,0,1]
	v_pk_fma_f32 v[208:209], v[192:193], v[172:173], v[208:209] op_sel_hi:[1,0,1]
	v_pk_fma_f32 v[206:207], v[190:191], v[172:173], v[206:207] op_sel_hi:[1,0,1]
	v_pk_fma_f32 v[204:205], v[188:189], v[172:173], v[204:205] op_sel_hi:[1,0,1]
	v_lshlrev_b32_e32 v132, 16, v63
	v_and_b32_e32 v133, 0xffff0000, v63
	v_lshlrev_b32_e32 v134, 16, v95
	v_and_b32_e32 v135, 0xffff0000, v95
	v_mul_f32_e32 v138, 0xbfb8aa3b, v134
	v_mul_f32_e32 v139, 0xbfb8aa3b, v135
	v_exp_f32_e32 v138, v138
	v_exp_f32_e32 v139, v139
	v_pk_fma_f32 v[136:137], v[204:205], v[152:153], v[132:133] op_sel_hi:[1,0,1] neg_lo:[0,0,1] neg_hi:[0,0,1]
	v_add_f32_e32 v138, 1.0, v138
	v_add_f32_e32 v139, 1.0, v139
	v_pk_mul_f32 v[136:137], v[130:131], v[136:137]
	v_div_scale_f32 v220, s[4:5], v138, v138, v134
	v_div_scale_f32 v225, s[4:5], v139, v139, v135
	v_rcp_f32_e32 v221, v220
	v_rcp_f32_e32 v144, v225
	s_nop 0
	v_fma_f32 v222, -v220, v221, 1.0
	v_fma_f32 v146, -v225, v144, 1.0
	v_fmac_f32_e32 v221, v222, v221
	v_fmac_f32_e32 v144, v146, v144
	v_div_scale_f32 v222, vcc, v134, v138, v134
	v_mul_f32_e32 v223, v222, v221
	v_fma_f32 v224, -v220, v223, v222
	v_fmac_f32_e32 v223, v224, v221
	v_fma_f32 v222, -v220, v223, v222
	s_nop 0
	v_div_fmas_f32 v222, v222, v221, v223
	v_div_scale_f32 v146, vcc, v135, v139, v135
	v_mul_f32_e32 v141, v146, v144
	v_fma_f32 v143, -v225, v141, v146
	v_fmac_f32_e32 v141, v143, v144
	v_fma_f32 v146, -v225, v141, v146
	v_div_fixup_f32 v134, v222, v138, v134
	v_div_fmas_f32 v146, v146, v144, v141
	s_nop 0
	v_div_fixup_f32 v135, v146, v139, v135
	v_pk_mul_f32 v[136:137], v[134:135], v[136:137]
	s_nop 0
	v_cvt_pk_bf16_f32 v95, v136, v137
	v_lshlrev_b32_e32 v132, 16, v67
	v_and_b32_e32 v133, 0xffff0000, v67
	v_lshlrev_b32_e32 v134, 16, v99
	v_and_b32_e32 v135, 0xffff0000, v99
	v_mul_f32_e32 v138, 0xbfb8aa3b, v134
	v_mul_f32_e32 v139, 0xbfb8aa3b, v135
	v_exp_f32_e32 v138, v138
	v_exp_f32_e32 v139, v139
	v_pk_fma_f32 v[136:137], v[206:207], v[154:155], v[132:133] op_sel_hi:[1,0,1] neg_lo:[0,0,1] neg_hi:[0,0,1]
	v_add_f32_e32 v138, 1.0, v138
	v_add_f32_e32 v139, 1.0, v139
	v_pk_mul_f32 v[136:137], v[130:131], v[136:137]
	v_div_scale_f32 v220, s[4:5], v138, v138, v134
	v_div_scale_f32 v225, s[4:5], v139, v139, v135
	v_rcp_f32_e32 v221, v220
	v_rcp_f32_e32 v144, v225
	s_nop 0
	v_fma_f32 v222, -v220, v221, 1.0
	v_fma_f32 v146, -v225, v144, 1.0
	v_fmac_f32_e32 v221, v222, v221
	v_fmac_f32_e32 v144, v146, v144
	v_div_scale_f32 v222, vcc, v134, v138, v134
	v_mul_f32_e32 v223, v222, v221
	v_fma_f32 v224, -v220, v223, v222
	v_fmac_f32_e32 v223, v224, v221
	v_fma_f32 v222, -v220, v223, v222
	s_nop 0
	v_div_fmas_f32 v222, v222, v221, v223
	v_div_scale_f32 v146, vcc, v135, v139, v135
	v_mul_f32_e32 v141, v146, v144
	v_fma_f32 v143, -v225, v141, v146
	v_fmac_f32_e32 v141, v143, v144
	v_fma_f32 v146, -v225, v141, v146
	v_div_fixup_f32 v134, v222, v138, v134
	v_div_fmas_f32 v146, v146, v144, v141
	s_nop 0
	v_div_fixup_f32 v135, v146, v139, v135
	v_pk_mul_f32 v[136:137], v[134:135], v[136:137]
	s_nop 0
	v_cvt_pk_bf16_f32 v99, v136, v137
	v_lshlrev_b32_e32 v132, 16, v71
	v_and_b32_e32 v133, 0xffff0000, v71
	v_lshlrev_b32_e32 v134, 16, v103
	v_and_b32_e32 v135, 0xffff0000, v103
	v_mul_f32_e32 v138, 0xbfb8aa3b, v134
	v_mul_f32_e32 v139, 0xbfb8aa3b, v135
	v_exp_f32_e32 v138, v138
	v_exp_f32_e32 v139, v139
	v_pk_fma_f32 v[136:137], v[208:209], v[156:157], v[132:133] op_sel_hi:[1,0,1] neg_lo:[0,0,1] neg_hi:[0,0,1]
	v_add_f32_e32 v138, 1.0, v138
	v_add_f32_e32 v139, 1.0, v139
	v_pk_mul_f32 v[136:137], v[130:131], v[136:137]
	v_div_scale_f32 v220, s[4:5], v138, v138, v134
	v_div_scale_f32 v225, s[4:5], v139, v139, v135
	v_rcp_f32_e32 v221, v220
	v_rcp_f32_e32 v144, v225
	s_nop 0
	v_fma_f32 v222, -v220, v221, 1.0
	v_fma_f32 v146, -v225, v144, 1.0
	v_fmac_f32_e32 v221, v222, v221
	v_fmac_f32_e32 v144, v146, v144
	v_div_scale_f32 v222, vcc, v134, v138, v134
	v_mul_f32_e32 v223, v222, v221
	v_fma_f32 v224, -v220, v223, v222
	v_fmac_f32_e32 v223, v224, v221
	v_fma_f32 v222, -v220, v223, v222
	s_nop 0
	v_div_fmas_f32 v222, v222, v221, v223
	v_div_scale_f32 v146, vcc, v135, v139, v135
	v_mul_f32_e32 v141, v146, v144
	v_fma_f32 v143, -v225, v141, v146
	v_fmac_f32_e32 v141, v143, v144
	v_fma_f32 v146, -v225, v141, v146
	v_div_fixup_f32 v134, v222, v138, v134
	v_div_fmas_f32 v146, v146, v144, v141
	s_nop 0
	v_div_fixup_f32 v135, v146, v139, v135
	v_pk_mul_f32 v[136:137], v[134:135], v[136:137]
	s_nop 0
	v_cvt_pk_bf16_f32 v103, v136, v137
	v_lshlrev_b32_e32 v132, 16, v75
	v_and_b32_e32 v133, 0xffff0000, v75
	v_lshlrev_b32_e32 v134, 16, v107
	v_and_b32_e32 v135, 0xffff0000, v107
	v_mul_f32_e32 v138, 0xbfb8aa3b, v134
	v_mul_f32_e32 v139, 0xbfb8aa3b, v135
	v_exp_f32_e32 v138, v138
	v_exp_f32_e32 v139, v139
	v_pk_fma_f32 v[136:137], v[210:211], v[158:159], v[132:133] op_sel_hi:[1,0,1] neg_lo:[0,0,1] neg_hi:[0,0,1]
	v_add_f32_e32 v138, 1.0, v138
	v_add_f32_e32 v139, 1.0, v139
	v_pk_mul_f32 v[136:137], v[130:131], v[136:137]
	v_div_scale_f32 v220, s[4:5], v138, v138, v134
	v_div_scale_f32 v225, s[4:5], v139, v139, v135
	v_rcp_f32_e32 v221, v220
	v_rcp_f32_e32 v144, v225
	s_nop 0
	v_fma_f32 v222, -v220, v221, 1.0
	v_fma_f32 v146, -v225, v144, 1.0
	v_fmac_f32_e32 v221, v222, v221
	v_fmac_f32_e32 v144, v146, v144
	v_div_scale_f32 v222, vcc, v134, v138, v134
	v_mul_f32_e32 v223, v222, v221
	v_fma_f32 v224, -v220, v223, v222
	v_fmac_f32_e32 v223, v224, v221
	v_fma_f32 v222, -v220, v223, v222
	s_nop 0
	v_div_fmas_f32 v222, v222, v221, v223
	v_div_scale_f32 v146, vcc, v135, v139, v135
	v_mul_f32_e32 v141, v146, v144
	v_fma_f32 v143, -v225, v141, v146
	v_fmac_f32_e32 v141, v143, v144
	v_fma_f32 v146, -v225, v141, v146
	v_div_fixup_f32 v134, v222, v138, v134
	v_div_fmas_f32 v146, v146, v144, v141
	s_nop 0
	v_div_fixup_f32 v135, v146, v139, v135
	v_pk_mul_f32 v[136:137], v[134:135], v[136:137]
	s_nop 0
	v_cvt_pk_bf16_f32 v107, v136, v137
	v_lshlrev_b32_e32 v132, 16, v79
	v_and_b32_e32 v133, 0xffff0000, v79
	v_lshlrev_b32_e32 v134, 16, v111
	v_and_b32_e32 v135, 0xffff0000, v111
	v_mul_f32_e32 v138, 0xbfb8aa3b, v134
	v_mul_f32_e32 v139, 0xbfb8aa3b, v135
	v_exp_f32_e32 v138, v138
	v_exp_f32_e32 v139, v139
	v_pk_fma_f32 v[136:137], v[212:213], v[160:161], v[132:133] op_sel_hi:[1,0,1] neg_lo:[0,0,1] neg_hi:[0,0,1]
	v_add_f32_e32 v138, 1.0, v138
	v_add_f32_e32 v139, 1.0, v139
	v_pk_mul_f32 v[136:137], v[130:131], v[136:137]
	v_div_scale_f32 v220, s[4:5], v138, v138, v134
	v_div_scale_f32 v225, s[4:5], v139, v139, v135
	v_rcp_f32_e32 v221, v220
	v_rcp_f32_e32 v144, v225
	s_nop 0
	v_fma_f32 v222, -v220, v221, 1.0
	v_fma_f32 v146, -v225, v144, 1.0
	v_fmac_f32_e32 v221, v222, v221
	v_fmac_f32_e32 v144, v146, v144
	v_div_scale_f32 v222, vcc, v134, v138, v134
	v_mul_f32_e32 v223, v222, v221
	v_fma_f32 v224, -v220, v223, v222
	v_fmac_f32_e32 v223, v224, v221
	v_fma_f32 v222, -v220, v223, v222
	s_nop 0
	v_div_fmas_f32 v222, v222, v221, v223
	v_div_scale_f32 v146, vcc, v135, v139, v135
	v_mul_f32_e32 v141, v146, v144
	v_fma_f32 v143, -v225, v141, v146
	v_fmac_f32_e32 v141, v143, v144
	v_fma_f32 v146, -v225, v141, v146
	v_div_fixup_f32 v134, v222, v138, v134
	v_div_fmas_f32 v146, v146, v144, v141
	s_nop 0
	v_div_fixup_f32 v135, v146, v139, v135
	v_pk_mul_f32 v[136:137], v[134:135], v[136:137]
	s_nop 0
	v_cvt_pk_bf16_f32 v111, v136, v137
	v_lshlrev_b32_e32 v132, 16, v83
	v_and_b32_e32 v133, 0xffff0000, v83
	v_lshlrev_b32_e32 v134, 16, v115
	v_and_b32_e32 v135, 0xffff0000, v115
	v_mul_f32_e32 v138, 0xbfb8aa3b, v134
	v_mul_f32_e32 v139, 0xbfb8aa3b, v135
	v_exp_f32_e32 v138, v138
	v_exp_f32_e32 v139, v139
	v_pk_fma_f32 v[136:137], v[214:215], v[162:163], v[132:133] op_sel_hi:[1,0,1] neg_lo:[0,0,1] neg_hi:[0,0,1]
	v_add_f32_e32 v138, 1.0, v138
	v_add_f32_e32 v139, 1.0, v139
	v_pk_mul_f32 v[136:137], v[130:131], v[136:137]
	v_div_scale_f32 v220, s[4:5], v138, v138, v134
	v_div_scale_f32 v225, s[4:5], v139, v139, v135
	v_rcp_f32_e32 v221, v220
	v_rcp_f32_e32 v144, v225
	s_nop 0
	v_fma_f32 v222, -v220, v221, 1.0
	v_fma_f32 v146, -v225, v144, 1.0
	v_fmac_f32_e32 v221, v222, v221
	v_fmac_f32_e32 v144, v146, v144
	v_div_scale_f32 v222, vcc, v134, v138, v134
	v_mul_f32_e32 v223, v222, v221
	v_fma_f32 v224, -v220, v223, v222
	v_fmac_f32_e32 v223, v224, v221
	v_fma_f32 v222, -v220, v223, v222
	s_nop 0
	v_div_fmas_f32 v222, v222, v221, v223
	v_div_scale_f32 v146, vcc, v135, v139, v135
	v_mul_f32_e32 v141, v146, v144
	v_fma_f32 v143, -v225, v141, v146
	v_fmac_f32_e32 v141, v143, v144
	v_fma_f32 v146, -v225, v141, v146
	v_div_fixup_f32 v134, v222, v138, v134
	v_div_fmas_f32 v146, v146, v144, v141
	s_nop 0
	v_div_fixup_f32 v135, v146, v139, v135
	v_pk_mul_f32 v[136:137], v[134:135], v[136:137]
	s_nop 0
	v_cvt_pk_bf16_f32 v115, v136, v137
	v_lshlrev_b32_e32 v132, 16, v87
	v_and_b32_e32 v133, 0xffff0000, v87
	v_lshlrev_b32_e32 v134, 16, v119
	v_and_b32_e32 v135, 0xffff0000, v119
	v_mul_f32_e32 v138, 0xbfb8aa3b, v134
	v_mul_f32_e32 v139, 0xbfb8aa3b, v135
	v_exp_f32_e32 v138, v138
	v_exp_f32_e32 v139, v139
	v_pk_fma_f32 v[136:137], v[216:217], v[164:165], v[132:133] op_sel_hi:[1,0,1] neg_lo:[0,0,1] neg_hi:[0,0,1]
	v_add_f32_e32 v138, 1.0, v138
	v_add_f32_e32 v139, 1.0, v139
	v_pk_mul_f32 v[136:137], v[130:131], v[136:137]
	v_div_scale_f32 v220, s[4:5], v138, v138, v134
	v_div_scale_f32 v225, s[4:5], v139, v139, v135
	v_rcp_f32_e32 v221, v220
	v_rcp_f32_e32 v144, v225
	s_nop 0
	v_fma_f32 v222, -v220, v221, 1.0
	v_fma_f32 v146, -v225, v144, 1.0
	v_fmac_f32_e32 v221, v222, v221
	v_fmac_f32_e32 v144, v146, v144
	v_div_scale_f32 v222, vcc, v134, v138, v134
	v_mul_f32_e32 v223, v222, v221
	v_fma_f32 v224, -v220, v223, v222
	v_fmac_f32_e32 v223, v224, v221
	v_fma_f32 v222, -v220, v223, v222
	s_nop 0
	v_div_fmas_f32 v222, v222, v221, v223
	v_div_scale_f32 v146, vcc, v135, v139, v135
	v_mul_f32_e32 v141, v146, v144
	v_fma_f32 v143, -v225, v141, v146
	v_fmac_f32_e32 v141, v143, v144
	v_fma_f32 v146, -v225, v141, v146
	v_div_fixup_f32 v134, v222, v138, v134
	v_div_fmas_f32 v146, v146, v144, v141
	s_nop 0
	v_div_fixup_f32 v135, v146, v139, v135
	v_pk_mul_f32 v[136:137], v[134:135], v[136:137]
	s_nop 0
	v_cvt_pk_bf16_f32 v119, v136, v137
	v_lshlrev_b32_e32 v132, 16, v91
	v_and_b32_e32 v133, 0xffff0000, v91
	v_lshlrev_b32_e32 v134, 16, v123
	v_and_b32_e32 v135, 0xffff0000, v123
	v_mul_f32_e32 v138, 0xbfb8aa3b, v134
	v_mul_f32_e32 v139, 0xbfb8aa3b, v135
	v_exp_f32_e32 v138, v138
	v_exp_f32_e32 v139, v139
	v_pk_fma_f32 v[136:137], v[218:219], v[166:167], v[132:133] op_sel_hi:[1,0,1] neg_lo:[0,0,1] neg_hi:[0,0,1]
	v_add_f32_e32 v138, 1.0, v138
	v_add_f32_e32 v139, 1.0, v139
	v_pk_mul_f32 v[136:137], v[130:131], v[136:137]
	v_div_scale_f32 v220, s[4:5], v138, v138, v134
	v_div_scale_f32 v225, s[4:5], v139, v139, v135
	v_rcp_f32_e32 v221, v220
	v_rcp_f32_e32 v144, v225
	s_nop 0
	v_fma_f32 v222, -v220, v221, 1.0
	v_fma_f32 v146, -v225, v144, 1.0
	v_fmac_f32_e32 v221, v222, v221
	v_fmac_f32_e32 v144, v146, v144
	v_div_scale_f32 v222, vcc, v134, v138, v134
	v_mul_f32_e32 v223, v222, v221
	v_fma_f32 v224, -v220, v223, v222
	v_fmac_f32_e32 v223, v224, v221
	v_fma_f32 v222, -v220, v223, v222
	s_nop 0
	v_div_fmas_f32 v222, v222, v221, v223
	v_div_scale_f32 v146, vcc, v135, v139, v135
	v_mul_f32_e32 v141, v146, v144
	v_fma_f32 v143, -v225, v141, v146
	v_fmac_f32_e32 v141, v143, v144
	v_fma_f32 v146, -v225, v141, v146
	v_div_fixup_f32 v134, v222, v138, v134
	v_div_fmas_f32 v146, v146, v144, v141
	s_nop 0
	v_div_fixup_f32 v135, v146, v139, v135
	v_pk_mul_f32 v[136:137], v[134:135], v[136:137]
	s_nop 0
	v_cvt_pk_bf16_f32 v123, v136, v137
	s_add_i32 s0, s6, 15
	s_lshl_b32 s0, s0, 10
	v_and_b32_e32 v143, 63, v226
	v_lshlrev_b32_e32 v142, 4, v143
	v_add_u32_e32 v142, s0, v142
	global_store_dwordx4 v142, v[92:95], s[44:45]
	v_add_u32_e32 v142, 0x400, v142
	global_store_dwordx4 v142, v[96:99], s[44:45]
	v_add_u32_e32 v142, 0x400, v142
	global_store_dwordx4 v142, v[100:103], s[44:45]
	v_add_u32_e32 v142, 0x400, v142
	global_store_dwordx4 v142, v[104:107], s[44:45]
	v_add_u32_e32 v142, 0x400, v142
	global_store_dwordx4 v142, v[108:111], s[44:45]
	v_add_u32_e32 v142, 0x400, v142
	global_store_dwordx4 v142, v[112:115], s[44:45]
	v_add_u32_e32 v142, 0x400, v142
	global_store_dwordx4 v142, v[116:119], s[44:45]
	v_add_u32_e32 v142, 0x400, v142
	global_store_dwordx4 v142, v[120:123], s[44:45]
	v_readlane_b32 s0, v254, 49
	s_add_i32 s55, s55, s40
	s_add_i32 s54, s54, s0
	s_cmpk_gt_i32 s55, 0xff
	s_cbranch_scc0 .LBB0_298
